# score: sub-key fragment reads use two per-lane LDS bases + immediate offsets (mt*4352+ks*64); the 3 address VALU ops per read (192 per item) removed, MFMA->VALU wait states preserved
# baseline (speedup 1.0000x reference)
; __device__ void ph_score(const P& p, int* lds) {
;     ...
;   for (int it = blockIdx.x; it < 528 * 8; it += gridDim.x) {
;     const int h = it & 7, tile = it >> 3;
;     const size_t tok = (size_t)tile * 64 + w * 16 + fr;
;     float tv[2][16];
; #pragma unroll
;     for (int half = 0; half < 2; ++half) {
;       const u16* Kb = (half ? p_K2b : p_K1b) + h * 128 * 128;
;       f32x4 sc[8];
; #pragma unroll
;       for (int mt = 0; mt < 8; ++mt) sc[mt] = f32x4{0.f, 0.f, 0.f, 0.f};
; #pragma unroll
;       for (int ks = 0; ks < 4; ++ks) {
;         bf16x8 qf = *(const bf16x8*)(Qb + tok * 2048 + h * 256 + half * 128 + ks * 32 + fq * 8);
; #pragma unroll
;         for (int mt = 0; mt < 8; ++mt) {
;           bf16x8 kf = *(const bf16x8*)(Kb + (mt * 16 + fr) * 128 + ks * 32 + fq * 8);
.Lsc_keys_ok:
	v_and_b32_e32 v223, 15, v220
	v_bfe_u32 v224, v220, 4, 2
	v_mul_u32_u24_e32 v223, 0x110, v223
	v_lshl_add_u32 v223, v224, 4, v223
	v_add_u32_e32 v224, 0xa8d0, v223
	v_add_u32_e32 v223, 0x2000, v223
	s_ashr_i32 s10, s82, 3
	s_ashr_i32 s11, s10, 31
	s_lshl_b64 s[10:11], s[10:11], 6
	v_lshl_add_u64 v[44:45], s[10:11], 0, v[16:17]
	s_and_b32 s83, s82, 7
	v_lshlrev_b64 v[0:1], 12, v[44:45]
	v_lshl_add_u64 v[0:1], s[2:3], 0, v[0:1]
	s_lshl_b32 s70, s83, 9
	v_lshl_add_u64 v[0:1], v[0:1], 0, s[70:71]
	s_lshl_b32 s70, s83, 15
	v_lshl_add_u64 v[14:15], v[22:23], 0, s[70:71]
	v_lshl_add_u64 v[46:47], v[14:15], 0, v[28:29]
	v_lshl_add_u64 v[0:1], v[0:1], 0, v[26:27]
	v_lshl_add_u64 v[10:11], v[14:15], 0, v[30:31]
	v_lshl_add_u64 v[50:51], v[14:15], 0, v[32:33]
	v_lshl_add_u64 v[154:155], v[14:15], 0, v[34:35]
	v_lshl_add_u64 v[166:167], v[14:15], 0, v[36:37]
	v_lshl_add_u64 v[170:171], v[14:15], 0, v[38:39]
	v_lshl_add_u64 v[174:175], v[14:15], 0, v[40:41]
	v_lshl_add_u64 v[178:179], v[14:15], 0, v[42:43]


; __device__ __forceinline__ f32x4 mfma16(bf16x8 a, bf16x8 b, f32x4 c) { return __builtin_amdgcn_mfma_f32_16x16x32_bf16(a, b, c, 0, 0, 0); }
; __device__ void ph_score(const P& p, int* lds) {
;     ...
;       for (int ks = 0; ks < 4; ++ks) {
;         bf16x8 qf = *(const bf16x8*)(Qb + tok * 2048 + h * 256 + half * 128 + ks * 32 + fq * 8);
; #pragma unroll
;         for (int mt = 0; mt < 8; ++mt) {
;           bf16x8 kf = *(const bf16x8*)(Kb + (mt * 16 + fr) * 128 + ks * 32 + fq * 8);
;           sc[mt] = mfma16(kf, qf, sc[mt]);
	ds_read_b128 v[2:5], v223 offset:0
	global_load_dwordx4 v[6:9], v[0:1], off
	global_load_dword v218, v[0:1], off offset:128
	global_load_dword v219, v[0:1], off offset:256
	global_load_dword v225, v[0:1], off offset:384
	v_lshl_add_u64 v[194:195], v[14:15], 0, 64


; __device__ __forceinline__ f32x4 mfma16(bf16x8 a, bf16x8 b, f32x4 c) { return __builtin_amdgcn_mfma_f32_16x16x32_bf16(a, b, c, 0, 0, 0); }
; __device__ void ph_score(const P& p, int* lds) {
;     ...
;       for (int ks = 0; ks < 4; ++ks) {
;         bf16x8 qf = *(const bf16x8*)(Qb + tok * 2048 + h * 256 + half * 128 + ks * 32 + fq * 8);
; #pragma unroll
;         for (int mt = 0; mt < 8; ++mt) {
;           bf16x8 kf = *(const bf16x8*)(Kb + (mt * 16 + fr) * 128 + ks * 32 + fq * 8);
;           sc[mt] = mfma16(kf, qf, sc[mt]);
	ds_read_b128 v[10:13], v223 offset:4352
	v_lshl_add_u64 v[182:183], v[194:195], 0, v[30:31]


; __device__ __forceinline__ f32x4 mfma16(bf16x8 a, bf16x8 b, f32x4 c) { return __builtin_amdgcn_mfma_f32_16x16x32_bf16(a, b, c, 0, 0, 0); }
; __device__ void ph_score(const P& p, int* lds) {
;     ...
;       for (int ks = 0; ks < 4; ++ks) {
;         bf16x8 qf = *(const bf16x8*)(Qb + tok * 2048 + h * 256 + half * 128 + ks * 32 + fq * 8);
; #pragma unroll
;         for (int mt = 0; mt < 8; ++mt) {
;           bf16x8 kf = *(const bf16x8*)(Kb + (mt * 16 + fr) * 128 + ks * 32 + fq * 8);
;           sc[mt] = mfma16(kf, qf, sc[mt]);
	ds_read_b128 v[50:53], v223 offset:8704
	v_lshl_add_u64 v[186:187], v[194:195], 0, v[32:33]


; __device__ __forceinline__ f32x4 mfma16(bf16x8 a, bf16x8 b, f32x4 c) { return __builtin_amdgcn_mfma_f32_16x16x32_bf16(a, b, c, 0, 0, 0); }
; __device__ void ph_score(const P& p, int* lds) {
;     ...
;       for (int ks = 0; ks < 4; ++ks) {
;         bf16x8 qf = *(const bf16x8*)(Qb + tok * 2048 + h * 256 + half * 128 + ks * 32 + fq * 8);
; #pragma unroll
;         for (int mt = 0; mt < 8; ++mt) {
;           bf16x8 kf = *(const bf16x8*)(Kb + (mt * 16 + fr) * 128 + ks * 32 + fq * 8);
;           sc[mt] = mfma16(kf, qf, sc[mt]);
	ds_read_b128 v[154:157], v223 offset:13056
	s_nop 0
	global_load_dwordx4 v[158:161], v[0:1], off offset:64


; __device__ __forceinline__ f32x4 mfma16(bf16x8 a, bf16x8 b, f32x4 c) { return __builtin_amdgcn_mfma_f32_16x16x32_bf16(a, b, c, 0, 0, 0); }
; __device__ void ph_score(const P& p, int* lds) {
;     ...
;       for (int ks = 0; ks < 4; ++ks) {
;         bf16x8 qf = *(const bf16x8*)(Qb + tok * 2048 + h * 256 + half * 128 + ks * 32 + fq * 8);
; #pragma unroll
;         for (int mt = 0; mt < 8; ++mt) {
;           bf16x8 kf = *(const bf16x8*)(Kb + (mt * 16 + fr) * 128 + ks * 32 + fq * 8);
;           sc[mt] = mfma16(kf, qf, sc[mt]);
	ds_read_b128 v[162:165], v223 offset:64
	v_lshl_add_u64 v[190:191], v[194:195], 0, v[34:35]


; __device__ __forceinline__ f32x4 mfma16(bf16x8 a, bf16x8 b, f32x4 c) { return __builtin_amdgcn_mfma_f32_16x16x32_bf16(a, b, c, 0, 0, 0); }
; __device__ void ph_score(const P& p, int* lds) {
;     ...
;       for (int ks = 0; ks < 4; ++ks) {
;         bf16x8 qf = *(const bf16x8*)(Qb + tok * 2048 + h * 256 + half * 128 + ks * 32 + fq * 8);
; #pragma unroll
;         for (int mt = 0; mt < 8; ++mt) {
;           bf16x8 kf = *(const bf16x8*)(Kb + (mt * 16 + fr) * 128 + ks * 32 + fq * 8);
;           sc[mt] = mfma16(kf, qf, sc[mt]);
	ds_read_b128 v[166:169], v223 offset:17408
	v_lshl_add_u64 v[196:197], v[194:195], 0, v[36:37]


; __device__ __forceinline__ f32x4 mfma16(bf16x8 a, bf16x8 b, f32x4 c) { return __builtin_amdgcn_mfma_f32_16x16x32_bf16(a, b, c, 0, 0, 0); }
; __device__ void ph_score(const P& p, int* lds) {
;     ...
;       for (int ks = 0; ks < 4; ++ks) {
;         bf16x8 qf = *(const bf16x8*)(Qb + tok * 2048 + h * 256 + half * 128 + ks * 32 + fq * 8);
; #pragma unroll
;         for (int mt = 0; mt < 8; ++mt) {
;           bf16x8 kf = *(const bf16x8*)(Kb + (mt * 16 + fr) * 128 + ks * 32 + fq * 8);
;           sc[mt] = mfma16(kf, qf, sc[mt]);
	ds_read_b128 v[170:173], v223 offset:21760
	v_lshl_add_u64 v[202:203], v[14:15], 0, s[72:73]


; __device__ __forceinline__ f32x4 mfma16(bf16x8 a, bf16x8 b, f32x4 c) { return __builtin_amdgcn_mfma_f32_16x16x32_bf16(a, b, c, 0, 0, 0); }
; __device__ void ph_score(const P& p, int* lds) {
;     ...
;       for (int ks = 0; ks < 4; ++ks) {
;         bf16x8 qf = *(const bf16x8*)(Qb + tok * 2048 + h * 256 + half * 128 + ks * 32 + fq * 8);
; #pragma unroll
;         for (int mt = 0; mt < 8; ++mt) {
;           bf16x8 kf = *(const bf16x8*)(Kb + (mt * 16 + fr) * 128 + ks * 32 + fq * 8);
;           sc[mt] = mfma16(kf, qf, sc[mt]);
	ds_read_b128 v[174:177], v223 offset:26112
	v_lshl_add_u64 v[198:199], v[202:203], 0, v[30:31]


; __device__ __forceinline__ f32x4 mfma16(bf16x8 a, bf16x8 b, f32x4 c) { return __builtin_amdgcn_mfma_f32_16x16x32_bf16(a, b, c, 0, 0, 0); }
; __device__ void ph_score(const P& p, int* lds) {
;     ...
;       for (int ks = 0; ks < 4; ++ks) {
;         bf16x8 qf = *(const bf16x8*)(Qb + tok * 2048 + h * 256 + half * 128 + ks * 32 + fq * 8);
; #pragma unroll
;         for (int mt = 0; mt < 8; ++mt) {
;           bf16x8 kf = *(const bf16x8*)(Kb + (mt * 16 + fr) * 128 + ks * 32 + fq * 8);
;           sc[mt] = mfma16(kf, qf, sc[mt]);
	ds_read_b128 v[178:181], v223 offset:30464
	v_lshl_add_u64 v[204:205], v[202:203], 0, v[36:37]


; __device__ __forceinline__ f32x4 mfma16(bf16x8 a, bf16x8 b, f32x4 c) { return __builtin_amdgcn_mfma_f32_16x16x32_bf16(a, b, c, 0, 0, 0); }
; __device__ void ph_score(const P& p, int* lds) {
;     ...
;       for (int ks = 0; ks < 4; ++ks) {
;         bf16x8 qf = *(const bf16x8*)(Qb + tok * 2048 + h * 256 + half * 128 + ks * 32 + fq * 8);
; #pragma unroll
;         for (int mt = 0; mt < 8; ++mt) {
;           bf16x8 kf = *(const bf16x8*)(Kb + (mt * 16 + fr) * 128 + ks * 32 + fq * 8);
;           sc[mt] = mfma16(kf, qf, sc[mt]);
	ds_read_b128 v[182:185], v223 offset:4416
	v_lshl_add_u64 v[14:15], v[14:15], 0, s[76:77]


; __device__ __forceinline__ f32x4 mfma16(bf16x8 a, bf16x8 b, f32x4 c) { return __builtin_amdgcn_mfma_f32_16x16x32_bf16(a, b, c, 0, 0, 0); }
; __device__ void ph_score(const P& p, int* lds) {
;     ...
;       for (int ks = 0; ks < 4; ++ks) {
;         bf16x8 qf = *(const bf16x8*)(Qb + tok * 2048 + h * 256 + half * 128 + ks * 32 + fq * 8);
; #pragma unroll
;         for (int mt = 0; mt < 8; ++mt) {
;           bf16x8 kf = *(const bf16x8*)(Kb + (mt * 16 + fr) * 128 + ks * 32 + fq * 8);
;           sc[mt] = mfma16(kf, qf, sc[mt]);
	ds_read_b128 v[186:189], v223 offset:8768
	s_waitcnt vmcnt(0) lgkmcnt(0)
	v_mfma_f32_16x16x32_bf16 v[2:5], v[2:5], v[6:9], 0


; __device__ __forceinline__ f32x4 mfma16(bf16x8 a, bf16x8 b, f32x4 c) { return __builtin_amdgcn_mfma_f32_16x16x32_bf16(a, b, c, 0, 0, 0); }
; __device__ void ph_score(const P& p, int* lds) {
;     ...
;       for (int ks = 0; ks < 4; ++ks) {
;         bf16x8 qf = *(const bf16x8*)(Qb + tok * 2048 + h * 256 + half * 128 + ks * 32 + fq * 8);
; #pragma unroll
;         for (int mt = 0; mt < 8; ++mt) {
;           bf16x8 kf = *(const bf16x8*)(Kb + (mt * 16 + fr) * 128 + ks * 32 + fq * 8);
;           sc[mt] = mfma16(kf, qf, sc[mt]);
	ds_read_b128 v[190:193], v223 offset:13120
	v_mfma_f32_16x16x32_bf16 v[10:13], v[10:13], v[6:9], 0
	v_mfma_f32_16x16x32_bf16 v[50:53], v[50:53], v[6:9], 0
	v_mfma_f32_16x16x32_bf16 v[154:157], v[154:157], v[6:9], 0
	v_mfma_f32_16x16x32_bf16 v[166:169], v[166:169], v[6:9], 0
	v_mfma_f32_16x16x32_bf16 v[170:173], v[170:173], v[6:9], 0
	v_mfma_f32_16x16x32_bf16 v[174:177], v[174:177], v[6:9], 0
	v_mfma_f32_16x16x32_bf16 v[6:9], v[178:181], v[6:9], 0


; __device__ __forceinline__ f32x4 mfma16(bf16x8 a, bf16x8 b, f32x4 c) { return __builtin_amdgcn_mfma_f32_16x16x32_bf16(a, b, c, 0, 0, 0); }
; __device__ void ph_score(const P& p, int* lds) {
;     ...
;       for (int ks = 0; ks < 4; ++ks) {
;         bf16x8 qf = *(const bf16x8*)(Qb + tok * 2048 + h * 256 + half * 128 + ks * 32 + fq * 8);
; #pragma unroll
;         for (int mt = 0; mt < 8; ++mt) {
;           bf16x8 kf = *(const bf16x8*)(Kb + (mt * 16 + fr) * 128 + ks * 32 + fq * 8);
;           sc[mt] = mfma16(kf, qf, sc[mt]);
	ds_read_b128 v[178:181], v223 offset:17472
	v_lshl_add_u64 v[196:197], v[194:195], 0, v[38:39]
	v_mfma_f32_16x16x32_bf16 v[2:5], v[162:165], v[158:161], v[2:5]


; __device__ __forceinline__ f32x4 mfma16(bf16x8 a, bf16x8 b, f32x4 c) { return __builtin_amdgcn_mfma_f32_16x16x32_bf16(a, b, c, 0, 0, 0); }
; __device__ void ph_score(const P& p, int* lds) {
;     ...
;       for (int ks = 0; ks < 4; ++ks) {
;         bf16x8 qf = *(const bf16x8*)(Qb + tok * 2048 + h * 256 + half * 128 + ks * 32 + fq * 8);
; #pragma unroll
;         for (int mt = 0; mt < 8; ++mt) {
;           bf16x8 kf = *(const bf16x8*)(Kb + (mt * 16 + fr) * 128 + ks * 32 + fq * 8);
;           sc[mt] = mfma16(kf, qf, sc[mt]);
	ds_read_b128 v[162:165], v223 offset:21824
	v_lshl_add_u64 v[196:197], v[194:195], 0, v[40:41]
	v_lshl_add_u64 v[194:195], v[194:195], 0, v[42:43]
	v_mfma_f32_16x16x32_bf16 v[10:13], v[182:185], v[158:161], v[10:13]


; __device__ __forceinline__ f32x4 mfma16(bf16x8 a, bf16x8 b, f32x4 c) { return __builtin_amdgcn_mfma_f32_16x16x32_bf16(a, b, c, 0, 0, 0); }
; __device__ void ph_score(const P& p, int* lds) {
;     ...
;       for (int ks = 0; ks < 4; ++ks) {
;         bf16x8 qf = *(const bf16x8*)(Qb + tok * 2048 + h * 256 + half * 128 + ks * 32 + fq * 8);
; #pragma unroll
;         for (int mt = 0; mt < 8; ++mt) {
;           bf16x8 kf = *(const bf16x8*)(Kb + (mt * 16 + fr) * 128 + ks * 32 + fq * 8);
;           sc[mt] = mfma16(kf, qf, sc[mt]);
	ds_read_b128 v[182:185], v223 offset:26176
	v_mfma_f32_16x16x32_bf16 v[50:53], v[186:189], v[158:161], v[50:53]


; __device__ __forceinline__ f32x4 mfma16(bf16x8 a, bf16x8 b, f32x4 c) { return __builtin_amdgcn_mfma_f32_16x16x32_bf16(a, b, c, 0, 0, 0); }
; __device__ void ph_score(const P& p, int* lds) {
;     ...
;       for (int ks = 0; ks < 4; ++ks) {
;         bf16x8 qf = *(const bf16x8*)(Qb + tok * 2048 + h * 256 + half * 128 + ks * 32 + fq * 8);
; #pragma unroll
;         for (int mt = 0; mt < 8; ++mt) {
;           bf16x8 kf = *(const bf16x8*)(Kb + (mt * 16 + fr) * 128 + ks * 32 + fq * 8);
;           sc[mt] = mfma16(kf, qf, sc[mt]);
	ds_read_b128 v[186:189], v223 offset:30528
	s_nop 0


; __device__ __forceinline__ f32x4 mfma16(bf16x8 a, bf16x8 b, f32x4 c) { return __builtin_amdgcn_mfma_f32_16x16x32_bf16(a, b, c, 0, 0, 0); }
; __device__ void ph_score(const P& p, int* lds) {
;     ...
;       for (int ks = 0; ks < 4; ++ks) {
;         bf16x8 qf = *(const bf16x8*)(Qb + tok * 2048 + h * 256 + half * 128 + ks * 32 + fq * 8);
; #pragma unroll
;         for (int mt = 0; mt < 8; ++mt) {
;           bf16x8 kf = *(const bf16x8*)(Kb + (mt * 16 + fr) * 128 + ks * 32 + fq * 8);
;           sc[mt] = mfma16(kf, qf, sc[mt]);
	ds_read_b128 v[194:197], v223 offset:128
	s_waitcnt vmcnt(0) lgkmcnt(0)
	v_mfma_f32_16x16x32_bf16 v[154:157], v[190:193], v[158:161], v[154:157]
	global_load_dwordx4 v[190:193], v[0:1], off offset:128
	v_mfma_f32_16x16x32_bf16 v[166:169], v[178:181], v[158:161], v[166:169]


; __device__ __forceinline__ f32x4 mfma16(bf16x8 a, bf16x8 b, f32x4 c) { return __builtin_amdgcn_mfma_f32_16x16x32_bf16(a, b, c, 0, 0, 0); }
; __device__ void ph_score(const P& p, int* lds) {
;     ...
;       for (int ks = 0; ks < 4; ++ks) {
;         bf16x8 qf = *(const bf16x8*)(Qb + tok * 2048 + h * 256 + half * 128 + ks * 32 + fq * 8);
; #pragma unroll
;         for (int mt = 0; mt < 8; ++mt) {
;           bf16x8 kf = *(const bf16x8*)(Kb + (mt * 16 + fr) * 128 + ks * 32 + fq * 8);
;           sc[mt] = mfma16(kf, qf, sc[mt]);
	ds_read_b128 v[178:181], v223 offset:4480
	v_lshl_add_u64 v[198:199], v[202:203], 0, v[32:33]
	v_mfma_f32_16x16x32_bf16 v[162:165], v[162:165], v[158:161], v[170:173]
	s_nop 2


; __device__ __forceinline__ f32x4 mfma16(bf16x8 a, bf16x8 b, f32x4 c) { return __builtin_amdgcn_mfma_f32_16x16x32_bf16(a, b, c, 0, 0, 0); }
; __device__ void ph_score(const P& p, int* lds) {
;     ...
;       for (int ks = 0; ks < 4; ++ks) {
;         bf16x8 qf = *(const bf16x8*)(Qb + tok * 2048 + h * 256 + half * 128 + ks * 32 + fq * 8);
; #pragma unroll
;         for (int mt = 0; mt < 8; ++mt) {
;           bf16x8 kf = *(const bf16x8*)(Kb + (mt * 16 + fr) * 128 + ks * 32 + fq * 8);
;           sc[mt] = mfma16(kf, qf, sc[mt]);
	ds_read_b128 v[170:173], v223 offset:8832
	v_lshl_add_u64 v[198:199], v[202:203], 0, v[34:35]
	v_mfma_f32_16x16x32_bf16 v[174:177], v[182:185], v[158:161], v[174:177]


; __device__ __forceinline__ f32x4 mfma16(bf16x8 a, bf16x8 b, f32x4 c) { return __builtin_amdgcn_mfma_f32_16x16x32_bf16(a, b, c, 0, 0, 0); }
; __device__ void ph_score(const P& p, int* lds) {
;     ...
;       for (int ks = 0; ks < 4; ++ks) {
;         bf16x8 qf = *(const bf16x8*)(Qb + tok * 2048 + h * 256 + half * 128 + ks * 32 + fq * 8);
; #pragma unroll
;         for (int mt = 0; mt < 8; ++mt) {
;           bf16x8 kf = *(const bf16x8*)(Kb + (mt * 16 + fr) * 128 + ks * 32 + fq * 8);
;           sc[mt] = mfma16(kf, qf, sc[mt]);
	ds_read_b128 v[182:185], v223 offset:13184
	s_nop 0
	global_load_dwordx4 v[198:201], v[0:1], off offset:192
	v_mfma_f32_16x16x32_bf16 v[6:9], v[186:189], v[158:161], v[6:9]


; __device__ __forceinline__ f32x4 mfma16(bf16x8 a, bf16x8 b, f32x4 c) { return __builtin_amdgcn_mfma_f32_16x16x32_bf16(a, b, c, 0, 0, 0); }
; __device__ void ph_score(const P& p, int* lds) {
;     ...
;       for (int ks = 0; ks < 4; ++ks) {
;         bf16x8 qf = *(const bf16x8*)(Qb + tok * 2048 + h * 256 + half * 128 + ks * 32 + fq * 8);
; #pragma unroll
;         for (int mt = 0; mt < 8; ++mt) {
;           bf16x8 kf = *(const bf16x8*)(Kb + (mt * 16 + fr) * 128 + ks * 32 + fq * 8);
;           sc[mt] = mfma16(kf, qf, sc[mt]);
	ds_read_b128 v[186:189], v223 offset:192
	v_lshl_add_u64 v[46:47], v[202:203], 0, v[40:41]


; __device__ __forceinline__ f32x4 mfma16(bf16x8 a, bf16x8 b, f32x4 c) { return __builtin_amdgcn_mfma_f32_16x16x32_bf16(a, b, c, 0, 0, 0); }
; __device__ void ph_score(const P& p, int* lds) {
;     ...
;       for (int ks = 0; ks < 4; ++ks) {
;         bf16x8 qf = *(const bf16x8*)(Qb + tok * 2048 + h * 256 + half * 128 + ks * 32 + fq * 8);
; #pragma unroll
;         for (int mt = 0; mt < 8; ++mt) {
;           bf16x8 kf = *(const bf16x8*)(Kb + (mt * 16 + fr) * 128 + ks * 32 + fq * 8);
;           sc[mt] = mfma16(kf, qf, sc[mt]);
	ds_read_b128 v[158:161], v223 offset:17536
	s_waitcnt vmcnt(0) lgkmcnt(0)
	v_mfma_f32_16x16x32_bf16 v[2:5], v[194:197], v[190:193], v[2:5]
	v_mfma_f32_16x16x32_bf16 v[10:13], v[178:181], v[190:193], v[10:13]


; __device__ __forceinline__ f32x4 mfma16(bf16x8 a, bf16x8 b, f32x4 c) { return __builtin_amdgcn_mfma_f32_16x16x32_bf16(a, b, c, 0, 0, 0); }
; __device__ void ph_score(const P& p, int* lds) {
;     ...
;       for (int ks = 0; ks < 4; ++ks) {
;         bf16x8 qf = *(const bf16x8*)(Qb + tok * 2048 + h * 256 + half * 128 + ks * 32 + fq * 8);
; #pragma unroll
;         for (int mt = 0; mt < 8; ++mt) {
;           bf16x8 kf = *(const bf16x8*)(Kb + (mt * 16 + fr) * 128 + ks * 32 + fq * 8);
;           sc[mt] = mfma16(kf, qf, sc[mt]);
	ds_read_b128 v[178:181], v223 offset:26240
	v_lshl_add_u64 v[204:205], v[202:203], 0, v[38:39]


; __device__ __forceinline__ f32x4 mfma16(bf16x8 a, bf16x8 b, f32x4 c) { return __builtin_amdgcn_mfma_f32_16x16x32_bf16(a, b, c, 0, 0, 0); }
; __device__ void ph_score(const P& p, int* lds) {
;     ...
;       for (int ks = 0; ks < 4; ++ks) {
;         bf16x8 qf = *(const bf16x8*)(Qb + tok * 2048 + h * 256 + half * 128 + ks * 32 + fq * 8);
; #pragma unroll
;         for (int mt = 0; mt < 8; ++mt) {
;           bf16x8 kf = *(const bf16x8*)(Kb + (mt * 16 + fr) * 128 + ks * 32 + fq * 8);
;           sc[mt] = mfma16(kf, qf, sc[mt]);
	ds_read_b128 v[194:197], v223 offset:21888
	v_lshl_add_u64 v[46:47], v[202:203], 0, v[42:43]
	v_mfma_f32_16x16x32_bf16 v[50:53], v[170:173], v[190:193], v[50:53]


; __device__ __forceinline__ f32x4 mfma16(bf16x8 a, bf16x8 b, f32x4 c) { return __builtin_amdgcn_mfma_f32_16x16x32_bf16(a, b, c, 0, 0, 0); }
; __device__ void ph_score(const P& p, int* lds) {
;     ...
;       for (int ks = 0; ks < 4; ++ks) {
;         bf16x8 qf = *(const bf16x8*)(Qb + tok * 2048 + h * 256 + half * 128 + ks * 32 + fq * 8);
; #pragma unroll
;         for (int mt = 0; mt < 8; ++mt) {
;           bf16x8 kf = *(const bf16x8*)(Kb + (mt * 16 + fr) * 128 + ks * 32 + fq * 8);
;           sc[mt] = mfma16(kf, qf, sc[mt]);
	ds_read_b128 v[170:173], v223 offset:30592
	v_lshl_add_u64 v[46:47], v[14:15], 0, v[30:31]
	v_mfma_f32_16x16x32_bf16 v[154:157], v[182:185], v[190:193], v[154:157]


; __device__ __forceinline__ f32x4 mfma16(bf16x8 a, bf16x8 b, f32x4 c) { return __builtin_amdgcn_mfma_f32_16x16x32_bf16(a, b, c, 0, 0, 0); }
; __device__ void ph_score(const P& p, int* lds) {
;     ...
;       for (int ks = 0; ks < 4; ++ks) {
;         bf16x8 qf = *(const bf16x8*)(Qb + tok * 2048 + h * 256 + half * 128 + ks * 32 + fq * 8);
; #pragma unroll
;         for (int mt = 0; mt < 8; ++mt) {
;           bf16x8 kf = *(const bf16x8*)(Kb + (mt * 16 + fr) * 128 + ks * 32 + fq * 8);
;           sc[mt] = mfma16(kf, qf, sc[mt]);
	ds_read_b128 v[182:185], v223 offset:4544
	v_lshl_add_u64 v[46:47], v[14:15], 0, v[32:33]
	v_mfma_f32_16x16x32_bf16 v[158:161], v[158:161], v[190:193], v[166:169]
	s_nop 2


; __device__ __forceinline__ f32x4 mfma16(bf16x8 a, bf16x8 b, f32x4 c) { return __builtin_amdgcn_mfma_f32_16x16x32_bf16(a, b, c, 0, 0, 0); }
; __device__ void ph_score(const P& p, int* lds) {
;     ...
;       for (int ks = 0; ks < 4; ++ks) {
;         bf16x8 qf = *(const bf16x8*)(Qb + tok * 2048 + h * 256 + half * 128 + ks * 32 + fq * 8);
; #pragma unroll
;         for (int mt = 0; mt < 8; ++mt) {
;           bf16x8 kf = *(const bf16x8*)(Kb + (mt * 16 + fr) * 128 + ks * 32 + fq * 8);
;           sc[mt] = mfma16(kf, qf, sc[mt]);
	ds_read_b128 v[166:169], v223 offset:8896
	v_lshl_add_u64 v[46:47], v[14:15], 0, v[36:37]
	v_mfma_f32_16x16x32_bf16 v[2:5], v[186:189], v[198:201], v[2:5]
	s_waitcnt vmcnt(0) lgkmcnt(0)
	v_mfma_f32_16x16x32_bf16 v[174:177], v[178:181], v[190:193], v[174:177]
	v_mfma_f32_16x16x32_bf16 v[162:165], v[194:197], v[190:193], v[162:165]


; __device__ __forceinline__ f32x4 mfma16(bf16x8 a, bf16x8 b, f32x4 c) { return __builtin_amdgcn_mfma_f32_16x16x32_bf16(a, b, c, 0, 0, 0); }
; __device__ void ph_score(const P& p, int* lds) {
;     ...
;       for (int ks = 0; ks < 4; ++ks) {
;         bf16x8 qf = *(const bf16x8*)(Qb + tok * 2048 + h * 256 + half * 128 + ks * 32 + fq * 8);
; #pragma unroll
;         for (int mt = 0; mt < 8; ++mt) {
;           bf16x8 kf = *(const bf16x8*)(Kb + (mt * 16 + fr) * 128 + ks * 32 + fq * 8);
;           sc[mt] = mfma16(kf, qf, sc[mt]);
	ds_read_b128 v[194:197], v223 offset:17600
	v_lshl_add_u64 v[46:47], v[14:15], 0, v[34:35]


; __device__ __forceinline__ f32x4 mfma16(bf16x8 a, bf16x8 b, f32x4 c) { return __builtin_amdgcn_mfma_f32_16x16x32_bf16(a, b, c, 0, 0, 0); }
; __device__ void ph_score(const P& p, int* lds) {
;     ...
;       for (int ks = 0; ks < 4; ++ks) {
;         bf16x8 qf = *(const bf16x8*)(Qb + tok * 2048 + h * 256 + half * 128 + ks * 32 + fq * 8);
; #pragma unroll
;         for (int mt = 0; mt < 8; ++mt) {
;           bf16x8 kf = *(const bf16x8*)(Kb + (mt * 16 + fr) * 128 + ks * 32 + fq * 8);
;           sc[mt] = mfma16(kf, qf, sc[mt]);
	ds_read_b128 v[178:181], v223 offset:13248
	v_lshl_add_u64 v[46:47], v[14:15], 0, v[38:39]
	v_mfma_f32_16x16x32_bf16 v[6:9], v[170:173], v[190:193], v[6:9]


; __device__ __forceinline__ f32x4 mfma16(bf16x8 a, bf16x8 b, f32x4 c) { return __builtin_amdgcn_mfma_f32_16x16x32_bf16(a, b, c, 0, 0, 0); }
; __device__ void ph_score(const P& p, int* lds) {
;     ...
;       for (int ks = 0; ks < 4; ++ks) {
;         bf16x8 qf = *(const bf16x8*)(Qb + tok * 2048 + h * 256 + half * 128 + ks * 32 + fq * 8);
; #pragma unroll
;         for (int mt = 0; mt < 8; ++mt) {
;           bf16x8 kf = *(const bf16x8*)(Kb + (mt * 16 + fr) * 128 + ks * 32 + fq * 8);
;           sc[mt] = mfma16(kf, qf, sc[mt]);
	ds_read_b128 v[170:173], v223 offset:21952
	v_lshl_add_u64 v[46:47], v[14:15], 0, v[40:41]


; __device__ __forceinline__ f32x4 mfma16(bf16x8 a, bf16x8 b, f32x4 c) { return __builtin_amdgcn_mfma_f32_16x16x32_bf16(a, b, c, 0, 0, 0); }
; __device__ void ph_score(const P& p, int* lds) {
;     ...
;       for (int ks = 0; ks < 4; ++ks) {
;         bf16x8 qf = *(const bf16x8*)(Qb + tok * 2048 + h * 256 + half * 128 + ks * 32 + fq * 8);
; #pragma unroll
;         for (int mt = 0; mt < 8; ++mt) {
;           bf16x8 kf = *(const bf16x8*)(Kb + (mt * 16 + fr) * 128 + ks * 32 + fq * 8);
;           sc[mt] = mfma16(kf, qf, sc[mt]);
	ds_read_b128 v[186:189], v223 offset:26304
	v_lshl_add_u64 v[14:15], v[14:15], 0, v[42:43]
	v_mfma_f32_16x16x32_bf16 v[10:13], v[182:185], v[198:201], v[10:13]


; __device__ __forceinline__ f32x4 mfma16(bf16x8 a, bf16x8 b, f32x4 c) { return __builtin_amdgcn_mfma_f32_16x16x32_bf16(a, b, c, 0, 0, 0); }
; __device__ void ph_score(const P& p, int* lds) {
;     ...
;           bf16x8 kf = *(const bf16x8*)(Kb + (mt * 16 + fr) * 128 + ks * 32 + fq * 8);
;           sc[mt] = mfma16(kf, qf, sc[mt]);
;         }
;       }
;       int a[16], b[16];
; #pragma unroll
;       for (int mt = 0; mt < 4; ++mt)
; #pragma unroll
;         for (int r = 0; r < 4; ++r) {
;           a[mt * 4 + r] = key_pack(sc[mt][r], mt * 16 + fq * 4 + r, 0x7f);
;           b[mt * 4 + r] = key_pack(sc[mt + 4][r], (mt + 4) * 16 + fq * 4 + r, 0x7f);
;         }
;       sort16p(a);
	ds_read_b128 v[182:185], v223 offset:30656
	v_and_b32_e32 v14, 0xffffff80, v2
	v_ashrrev_i32_e32 v2, 31, v2
	v_and_b32_e32 v2, 0x7fffffff, v2
	v_bitop3_b32 v2, v14, v2, v20 bitop3:0x36
	v_mfma_f32_16x16x32_bf16 v[50:53], v[166:169], v[198:201], v[50:53]
	s_waitcnt vmcnt(0) lgkmcnt(0)
	v_mfma_f32_16x16x32_bf16 v[158:161], v[194:197], v[198:201], v[158:161]
	s_nop 7
	v_ashrrev_i32_e32 v15, 31, v158
	v_and_b32_e32 v14, 0xffffff80, v158
	v_and_b32_e32 v15, 0x7fffffff, v15
	v_bitop3_b32 v14, v14, v15, v56 bitop3:0x36
	v_and_b32_e32 v15, 0xffffff80, v3
	v_ashrrev_i32_e32 v3, 31, v3
	v_and_b32_e32 v3, 0x7fffffff, v3
	v_ashrrev_i32_e32 v18, 31, v159
	v_bitop3_b32 v3, v15, v3, v57 bitop3:0x36
	v_and_b32_e32 v15, 0xffffff80, v159
	v_and_b32_e32 v18, 0x7fffffff, v18
	v_bitop3_b32 v15, v15, v18, v58 bitop3:0x36
	v_and_b32_e32 v18, 0xffffff80, v4
	v_ashrrev_i32_e32 v4, 31, v4
	v_and_b32_e32 v4, 0x7fffffff, v4
	v_ashrrev_i32_e32 v46, 31, v160
	v_bitop3_b32 v4, v18, v4, v59 bitop3:0x36
	v_and_b32_e32 v18, 0xffffff80, v160
	v_and_b32_e32 v46, 0x7fffffff, v46
	v_mfma_f32_16x16x32_bf16 v[162:165], v[170:173], v[198:201], v[162:165]
	v_bitop3_b32 v18, v18, v46, v60 bitop3:0x36
	v_and_b32_e32 v46, 0xffffff80, v5
	v_ashrrev_i32_e32 v5, 31, v5
	v_and_b32_e32 v5, 0x7fffffff, v5
	v_ashrrev_i32_e32 v47, 31, v161
	v_bitop3_b32 v5, v46, v5, v61 bitop3:0x36
	v_and_b32_e32 v46, 0xffffff80, v161
	v_and_b32_e32 v47, 0x7fffffff, v47
	v_bitop3_b32 v46, v46, v47, v62 bitop3:0x36
	v_and_b32_e32 v47, 0xffffff80, v10
	v_ashrrev_i32_e32 v10, 31, v10
	v_and_b32_e32 v10, 0x7fffffff, v10
	v_ashrrev_i32_e32 v48, 31, v162
	v_bitop3_b32 v10, v47, v10, v63 bitop3:0x36
	v_and_b32_e32 v47, 0xffffff80, v162
	v_and_b32_e32 v48, 0x7fffffff, v48
	v_bitop3_b32 v47, v47, v48, v64 bitop3:0x36
	v_and_b32_e32 v48, 0xffffff80, v11
	v_ashrrev_i32_e32 v11, 31, v11
	v_and_b32_e32 v11, 0x7fffffff, v11
	v_ashrrev_i32_e32 v153, 31, v163
	v_bitop3_b32 v11, v48, v11, v65 bitop3:0x36
	v_and_b32_e32 v48, 0xffffff80, v163
	v_and_b32_e32 v153, 0x7fffffff, v153
	v_bitop3_b32 v48, v48, v153, v66 bitop3:0x36
	v_and_b32_e32 v153, 0xffffff80, v12
	v_ashrrev_i32_e32 v12, 31, v12
	v_and_b32_e32 v12, 0x7fffffff, v12
	v_ashrrev_i32_e32 v158, 31, v164
	v_bitop3_b32 v12, v153, v12, v67 bitop3:0x36
	v_and_b32_e32 v153, 0xffffff80, v164
	v_and_b32_e32 v158, 0x7fffffff, v158
	v_mfma_f32_16x16x32_bf16 v[166:169], v[186:189], v[198:201], v[174:177]
	v_bitop3_b32 v153, v153, v158, v68 bitop3:0x36
	v_and_b32_e32 v158, 0xffffff80, v13
	v_ashrrev_i32_e32 v13, 31, v13
	v_and_b32_e32 v13, 0x7fffffff, v13
	v_ashrrev_i32_e32 v159, 31, v165
	v_bitop3_b32 v13, v158, v13, v69 bitop3:0x36
	v_and_b32_e32 v158, 0xffffff80, v165
	v_and_b32_e32 v159, 0x7fffffff, v159
	v_bitop3_b32 v158, v158, v159, v70 bitop3:0x36
	v_and_b32_e32 v159, 0xffffff80, v50
	v_ashrrev_i32_e32 v50, 31, v50
	v_and_b32_e32 v50, 0x7fffffff, v50
	v_ashrrev_i32_e32 v160, 31, v166
	v_bitop3_b32 v50, v159, v50, v71 bitop3:0x36
	v_and_b32_e32 v159, 0xffffff80, v166
	v_and_b32_e32 v160, 0x7fffffff, v160
	v_bitop3_b32 v159, v159, v160, v72 bitop3:0x36
	v_and_b32_e32 v160, 0xffffff80, v51
	v_ashrrev_i32_e32 v51, 31, v51
	v_and_b32_e32 v51, 0x7fffffff, v51
	v_ashrrev_i32_e32 v161, 31, v167
	v_bitop3_b32 v51, v160, v51, v73 bitop3:0x36
	v_and_b32_e32 v160, 0xffffff80, v167
	v_and_b32_e32 v161, 0x7fffffff, v161
	v_bitop3_b32 v160, v160, v161, v74 bitop3:0x36
	v_and_b32_e32 v161, 0xffffff80, v52
	v_ashrrev_i32_e32 v52, 31, v52
	v_and_b32_e32 v52, 0x7fffffff, v52
	v_ashrrev_i32_e32 v162, 31, v168
	v_mfma_f32_16x16x32_bf16 v[154:157], v[178:181], v[198:201], v[154:157]
	v_bitop3_b32 v52, v161, v52, v75 bitop3:0x36
	v_and_b32_e32 v161, 0xffffff80, v168
	v_and_b32_e32 v162, 0x7fffffff, v162
	v_bitop3_b32 v161, v161, v162, v76 bitop3:0x36
	v_and_b32_e32 v162, 0xffffff80, v53
	v_ashrrev_i32_e32 v53, 31, v53
	v_mfma_f32_16x16x32_bf16 v[6:9], v[182:185], v[198:201], v[6:9]
	v_and_b32_e32 v53, 0x7fffffff, v53
	v_ashrrev_i32_e32 v163, 31, v169
	v_bitop3_b32 v53, v162, v53, v77 bitop3:0x36
	v_and_b32_e32 v162, 0xffffff80, v169
	v_and_b32_e32 v163, 0x7fffffff, v163
	v_bitop3_b32 v162, v162, v163, v78 bitop3:0x36
	v_and_b32_e32 v163, 0xffffff80, v154
	v_ashrrev_i32_e32 v154, 31, v154
	v_and_b32_e32 v154, 0x7fffffff, v154
	v_bitop3_b32 v154, v163, v154, v79 bitop3:0x36
	v_and_b32_e32 v163, 0xffffff80, v6
	v_ashrrev_i32_e32 v6, 31, v6
	v_and_b32_e32 v6, 0x7fffffff, v6
	v_bitop3_b32 v6, v163, v6, v80 bitop3:0x36
	v_and_b32_e32 v163, 0xffffff80, v155
	v_ashrrev_i32_e32 v155, 31, v155
	v_and_b32_e32 v155, 0x7fffffff, v155
	v_bitop3_b32 v155, v163, v155, v81 bitop3:0x36
	v_and_b32_e32 v163, 0xffffff80, v7
	v_ashrrev_i32_e32 v7, 31, v7
	v_and_b32_e32 v7, 0x7fffffff, v7
	v_bitop3_b32 v7, v163, v7, v82 bitop3:0x36
	v_and_b32_e32 v163, 0xffffff80, v156
	v_ashrrev_i32_e32 v156, 31, v156
	v_and_b32_e32 v156, 0x7fffffff, v156
	v_bitop3_b32 v156, v163, v156, v83 bitop3:0x36
	v_and_b32_e32 v163, 0xffffff80, v8
	v_ashrrev_i32_e32 v8, 31, v8
	v_and_b32_e32 v8, 0x7fffffff, v8
	v_bitop3_b32 v8, v163, v8, v84 bitop3:0x36
	v_and_b32_e32 v163, 0xffffff80, v157
	v_ashrrev_i32_e32 v157, 31, v157
	v_and_b32_e32 v157, 0x7fffffff, v157
	v_bitop3_b32 v157, v163, v157, v85 bitop3:0x36
	v_and_b32_e32 v163, 0xffffff80, v9
	v_ashrrev_i32_e32 v9, 31, v9
	v_and_b32_e32 v9, 0x7fffffff, v9
	v_bitop3_b32 v9, v163, v9, v86 bitop3:0x36
	v_max_i32_e32 v163, v2, v3
	v_min_i32_e32 v2, v2, v3
	v_max_i32_e32 v3, v5, v4
	v_min_i32_e32 v4, v5, v4
	v_max_i32_e32 v5, v10, v11
	v_min_i32_e32 v10, v10, v11
	v_max_i32_e32 v11, v13, v12
	v_min_i32_e32 v12, v13, v12
	v_max_i32_e32 v13, v50, v51
	v_min_i32_e32 v50, v50, v51
; __device__ __forceinline__ void sort16p(int (&v)[16]) {
; #pragma unroll
;   for (int k = 2; k <= 16; k <<= 1)
; #pragma unroll
;     for (int j = k >> 1; j > 0; j >>= 1)
; #pragma unroll
;       for (int i = 0; i < 16; ++i) {
;         int l = i ^ j;
;         if (l > i) {
;           if ((i & k) == 0) { CE1(v[i], v[l]); }
;           else { CE1(v[l], v[i]); }
;         }
;       }
; }
; __device__ void ph_score(const P& p, int* lds) {
;     ...
;       sort16p(a);
;       __builtin_amdgcn_sched_barrier(0);
;       sort16p(b);
	v_max_i32_e32 v51, v53, v52
	v_min_i32_e32 v52, v53, v52
	v_max_i32_e32 v53, v154, v155
	v_min_i32_e32 v154, v154, v155
	v_max_i32_e32 v155, v157, v156
	v_min_i32_e32 v156, v157, v156
	v_max_i32_e32 v157, v163, v4
	v_min_i32_e32 v4, v163, v4
	v_max_i32_e32 v163, v2, v3
	v_min_i32_e32 v2, v2, v3
	v_max_i32_e32 v3, v12, v5
	v_min_i32_e32 v5, v12, v5
	v_max_i32_e32 v12, v11, v10
	v_min_i32_e32 v10, v11, v10
	v_max_i32_e32 v11, v13, v52
	v_min_i32_e32 v13, v13, v52
	v_max_i32_e32 v52, v50, v51
	v_min_i32_e32 v50, v50, v51
	v_max_i32_e32 v51, v156, v53
	v_min_i32_e32 v53, v156, v53
	v_max_i32_e32 v156, v155, v154
	v_min_i32_e32 v154, v155, v154
	v_max_i32_e32 v155, v157, v163
	v_min_i32_e32 v157, v157, v163
	v_max_i32_e32 v163, v4, v2
	v_min_i32_e32 v2, v4, v2
	v_max_i32_e32 v4, v10, v5
	v_min_i32_e32 v5, v10, v5
	v_max_i32_e32 v10, v12, v3
	v_min_i32_e32 v3, v12, v3
	v_max_i32_e32 v12, v11, v52
	v_min_i32_e32 v11, v11, v52
	v_max_i32_e32 v52, v13, v50
	v_min_i32_e32 v13, v13, v50
	v_max_i32_e32 v50, v154, v53
	v_min_i32_e32 v53, v154, v53
	v_max_i32_e32 v154, v156, v51
	v_min_i32_e32 v51, v156, v51
	v_max_i32_e32 v156, v155, v5
	v_min_i32_e32 v5, v155, v5
	v_max_i32_e32 v155, v157, v4
	v_min_i32_e32 v4, v157, v4
	v_max_i32_e32 v157, v163, v3
	v_min_i32_e32 v3, v163, v3
	v_max_i32_e32 v163, v2, v10
	v_min_i32_e32 v2, v2, v10
	v_max_i32_e32 v10, v53, v12
	v_min_i32_e32 v12, v53, v12
	v_max_i32_e32 v53, v50, v11
	v_min_i32_e32 v11, v50, v11
	v_max_i32_e32 v50, v51, v52
	v_min_i32_e32 v51, v51, v52
	v_max_i32_e32 v52, v154, v13
	v_min_i32_e32 v13, v154, v13
	v_max_i32_e32 v154, v156, v157
	v_min_i32_e32 v156, v156, v157
	v_max_i32_e32 v157, v155, v163
	v_min_i32_e32 v155, v155, v163
	v_max_i32_e32 v163, v5, v3
	v_min_i32_e32 v3, v5, v3
	v_max_i32_e32 v5, v4, v2
	v_min_i32_e32 v2, v4, v2
	v_max_i32_e32 v4, v51, v12
	v_min_i32_e32 v12, v51, v12
	v_max_i32_e32 v51, v13, v11
	v_min_i32_e32 v11, v13, v11
	v_max_i32_e32 v13, v50, v10
	v_min_i32_e32 v10, v50, v10
	v_max_i32_e32 v50, v52, v53
	v_min_i32_e32 v52, v52, v53
	v_max_i32_e32 v53, v154, v157
	v_min_i32_e32 v154, v154, v157
	v_max_i32_e32 v157, v156, v155
	v_min_i32_e32 v155, v156, v155
	v_max_i32_e32 v156, v163, v5
	v_min_i32_e32 v5, v163, v5
	v_max_i32_e32 v163, v3, v2
	v_min_i32_e32 v2, v3, v2
	v_max_i32_e32 v3, v11, v12
	v_min_i32_e32 v11, v11, v12
	v_max_i32_e32 v12, v51, v4
	v_min_i32_e32 v4, v51, v4
	v_max_i32_e32 v51, v52, v10
	v_min_i32_e32 v10, v52, v10
	v_max_i32_e32 v52, v50, v13
	v_min_i32_e32 v13, v50, v13
	v_max_i32_e32 v50, v53, v11
	v_min_i32_e32 v11, v53, v11
	v_max_i32_e32 v53, v154, v3
	v_min_i32_e32 v3, v154, v3
	v_max_i32_e32 v154, v157, v4
	v_min_i32_e32 v4, v157, v4
	v_max_i32_e32 v157, v155, v12
	v_min_i32_e32 v12, v155, v12
	v_max_i32_e32 v155, v156, v10
	v_min_i32_e32 v10, v156, v10
	v_max_i32_e32 v156, v5, v51
	v_min_i32_e32 v5, v5, v51
	v_max_i32_e32 v51, v163, v13
	v_min_i32_e32 v13, v163, v13
	v_max_i32_e32 v163, v2, v52
	v_min_i32_e32 v2, v2, v52
	v_max_i32_e32 v52, v50, v155
	v_min_i32_e32 v50, v50, v155
	v_max_i32_e32 v155, v53, v156
	v_min_i32_e32 v53, v53, v156
	v_max_i32_e32 v156, v154, v51
	v_min_i32_e32 v51, v154, v51
	v_max_i32_e32 v154, v157, v163
	v_min_i32_e32 v157, v157, v163
	v_max_i32_e32 v163, v11, v10
	v_min_i32_e32 v10, v11, v10
	v_max_i32_e32 v11, v3, v5
	v_min_i32_e32 v3, v3, v5
	v_max_i32_e32 v5, v4, v13
	v_min_i32_e32 v4, v4, v13
	v_max_i32_e32 v13, v12, v2
	v_min_i32_e32 v2, v12, v2
	v_max_i32_e32 v12, v52, v156
	v_min_i32_e32 v52, v52, v156
	v_max_i32_e32 v156, v155, v154
	v_min_i32_e32 v154, v155, v154
	v_max_i32_e32 v155, v50, v51
	v_min_i32_e32 v50, v50, v51
	v_max_i32_e32 v51, v53, v157
	v_min_i32_e32 v53, v53, v157
	v_max_i32_e32 v157, v163, v5
	v_min_i32_e32 v5, v163, v5
	v_max_i32_e32 v163, v11, v13
	v_min_i32_e32 v11, v11, v13
	v_max_i32_e32 v13, v10, v4
	v_min_i32_e32 v4, v10, v4
	v_max_i32_e32 v10, v3, v2
	v_min_i32_e32 v2, v3, v2
	v_min_i32_e32 v3, v12, v156
	v_min_i32_e32 v164, v52, v154
	v_min_i32_e32 v165, v155, v51
	v_min_i32_e32 v166, v50, v53
	v_min_i32_e32 v167, v157, v163
	v_min_i32_e32 v168, v5, v11
	v_min_i32_e32 v169, v13, v10
	v_min_i32_e32 v170, v4, v2
	v_max_i32_e32 v171, v14, v15
	v_min_i32_e32 v14, v14, v15
	v_max_i32_e32 v15, v46, v18
	v_min_i32_e32 v18, v46, v18
	v_max_i32_e32 v46, v47, v48
	v_min_i32_e32 v47, v47, v48
	v_max_i32_e32 v48, v158, v153
	v_min_i32_e32 v153, v158, v153
	v_max_i32_e32 v158, v159, v160
	v_min_i32_e32 v159, v159, v160
	v_max_i32_e32 v160, v162, v161
	v_min_i32_e32 v161, v162, v161
	v_max_i32_e32 v162, v6, v7
	v_min_i32_e32 v6, v6, v7
	v_max_i32_e32 v7, v9, v8
	v_min_i32_e32 v8, v9, v8
	v_max_i32_e32 v9, v171, v18
	v_min_i32_e32 v18, v171, v18
	v_max_i32_e32 v171, v14, v15
	v_min_i32_e32 v14, v14, v15
	v_max_i32_e32 v15, v153, v46
	v_min_i32_e32 v46, v153, v46
	v_max_i32_e32 v153, v48, v47
	v_min_i32_e32 v47, v48, v47
	v_max_i32_e32 v48, v158, v161
	v_min_i32_e32 v158, v158, v161
	v_max_i32_e32 v161, v159, v160
	v_min_i32_e32 v159, v159, v160
	v_max_i32_e32 v160, v8, v162
	v_min_i32_e32 v8, v8, v162
	v_max_i32_e32 v162, v7, v6
	v_min_i32_e32 v6, v7, v6
	v_max_i32_e32 v7, v9, v171
	v_min_i32_e32 v9, v9, v171
	v_max_i32_e32 v171, v18, v14
	v_min_i32_e32 v14, v18, v14
	v_max_i32_e32 v18, v47, v46
	v_min_i32_e32 v46, v47, v46
	v_max_i32_e32 v47, v153, v15
	v_min_i32_e32 v15, v153, v15
	v_max_i32_e32 v153, v48, v161
	v_min_i32_e32 v48, v48, v161
	v_max_i32_e32 v161, v158, v159
	v_min_i32_e32 v158, v158, v159
	v_max_i32_e32 v159, v6, v8
	v_min_i32_e32 v6, v6, v8
	v_max_i32_e32 v8, v162, v160
	v_min_i32_e32 v160, v162, v160
	v_max_i32_e32 v162, v7, v46
	v_min_i32_e32 v7, v7, v46
; __device__ __forceinline__ void sort16p(int (&v)[16]) {
; #pragma unroll
;   for (int k = 2; k <= 16; k <<= 1)
; #pragma unroll
;     for (int j = k >> 1; j > 0; j >>= 1)
; #pragma unroll
;       for (int i = 0; i < 16; ++i) {
;         int l = i ^ j;
;         if (l > i) {
;           if ((i & k) == 0) { CE1(v[i], v[l]); }
;           else { CE1(v[l], v[i]); }
;         }
;       }
; }
; __device__ __forceinline__ void merge16p(int (&a)[16], const int (&b)[16]) {
; #pragma unroll
;   for (int i = 0; i < 16; ++i) a[i] = max(a[i], b[15 - i]);
; #pragma unroll
;   for (int j = 8; j > 0; j >>= 1)
; #pragma unroll
;     for (int i = 0; i < 16; ++i) {
;       int l = i ^ j;
;       if (l > i) { CE1(a[i], a[l]); }
;     }
; }
; __device__ __forceinline__ void xmerge16p(int (&a)[16], int mask) {
;   int b[16];
; #pragma unroll
;   for (int i = 0; i < 16; ++i) b[i] = (mask == 16) ? __builtin_amdgcn_ds_swizzle(a[i], 0x401F) : __shfl_xor(a[i], 32);
;   merge16p(a, b);
; }
	v_max_i32_e32 v46, v9, v18
	v_min_i32_e32 v9, v9, v18
	v_max_i32_e32 v18, v171, v15
	v_min_i32_e32 v15, v171, v15
	v_max_i32_e32 v171, v14, v47
	v_min_i32_e32 v14, v14, v47
	v_max_i32_e32 v47, v6, v153
	v_min_i32_e32 v6, v6, v153
	v_max_i32_e32 v153, v159, v48
	v_min_i32_e32 v48, v159, v48
	v_max_i32_e32 v159, v160, v161
	v_min_i32_e32 v160, v160, v161
	v_max_i32_e32 v161, v8, v158
	v_min_i32_e32 v8, v8, v158
	v_max_i32_e32 v158, v162, v18
	v_min_i32_e32 v18, v162, v18
	v_max_i32_e32 v162, v46, v171
	v_min_i32_e32 v46, v46, v171
	v_max_i32_e32 v171, v7, v15
	v_min_i32_e32 v7, v7, v15
	v_max_i32_e32 v15, v9, v14
	v_min_i32_e32 v9, v9, v14
	v_max_i32_e32 v14, v160, v6
	v_min_i32_e32 v6, v160, v6
	v_max_i32_e32 v160, v8, v48
	v_min_i32_e32 v8, v8, v48
	v_max_i32_e32 v48, v159, v47
	v_min_i32_e32 v47, v159, v47
	v_max_i32_e32 v159, v161, v153
	v_min_i32_e32 v153, v161, v153
	v_max_i32_e32 v161, v158, v162
	v_min_i32_e32 v158, v158, v162
	v_max_i32_e32 v162, v18, v46
	v_min_i32_e32 v18, v18, v46
	v_max_i32_e32 v46, v171, v15
	v_min_i32_e32 v15, v171, v15
	v_max_i32_e32 v171, v7, v9
	v_min_i32_e32 v7, v7, v9
	v_max_i32_e32 v9, v8, v6
	v_min_i32_e32 v6, v8, v6
	v_max_i32_e32 v8, v160, v14
	v_min_i32_e32 v14, v160, v14
	v_max_i32_e32 v160, v153, v47
	v_min_i32_e32 v47, v153, v47
	v_max_i32_e32 v153, v159, v48
	v_min_i32_e32 v48, v159, v48
	v_max_i32_e32 v159, v161, v6
	v_min_i32_e32 v6, v161, v6
	v_max_i32_e32 v161, v158, v9
	v_min_i32_e32 v9, v158, v9
	v_max_i32_e32 v158, v162, v14
	v_min_i32_e32 v14, v162, v14
	v_max_i32_e32 v162, v18, v8
	v_min_i32_e32 v8, v18, v8
	v_max_i32_e32 v18, v46, v47
	v_min_i32_e32 v46, v46, v47
	v_max_i32_e32 v47, v15, v160
	v_min_i32_e32 v15, v15, v160
	v_max_i32_e32 v160, v171, v48
	v_min_i32_e32 v48, v171, v48
	v_max_i32_e32 v171, v7, v153
	v_min_i32_e32 v7, v7, v153
	v_max_i32_e32 v153, v159, v18
	v_min_i32_e32 v18, v159, v18
	v_max_i32_e32 v159, v161, v47
	v_min_i32_e32 v47, v161, v47
	v_max_i32_e32 v161, v158, v160
	v_min_i32_e32 v158, v158, v160
	v_max_i32_e32 v160, v162, v171
	v_min_i32_e32 v162, v162, v171
	v_max_i32_e32 v171, v6, v46
	v_min_i32_e32 v6, v6, v46
	v_max_i32_e32 v46, v9, v15
	v_min_i32_e32 v9, v9, v15
	v_max_i32_e32 v15, v14, v48
	v_min_i32_e32 v14, v14, v48
	v_max_i32_e32 v48, v8, v7
	v_min_i32_e32 v7, v8, v7
	v_max_i32_e32 v8, v153, v161
	v_min_i32_e32 v153, v153, v161
	v_max_i32_e32 v161, v159, v160
	v_min_i32_e32 v159, v159, v160
	v_max_i32_e32 v160, v18, v158
	v_min_i32_e32 v18, v18, v158
	v_max_i32_e32 v158, v47, v162
	v_min_i32_e32 v47, v47, v162
	v_max_i32_e32 v162, v171, v15
	v_min_i32_e32 v15, v171, v15
	v_max_i32_e32 v171, v46, v48
	v_min_i32_e32 v46, v46, v48
	v_max_i32_e32 v48, v6, v14
	v_min_i32_e32 v6, v6, v14
	v_max_i32_e32 v14, v9, v7
	v_min_i32_e32 v7, v9, v7
	v_min_i32_e32 v9, v8, v161
	v_min_i32_e32 v172, v153, v159
	v_min_i32_e32 v173, v160, v158
	v_min_i32_e32 v174, v18, v47
	v_min_i32_e32 v175, v162, v171
	v_min_i32_e32 v176, v15, v46
	v_min_i32_e32 v177, v48, v14
	v_min_i32_e32 v178, v6, v7
	v_max3_i32 v12, v12, v156, v178
	v_max3_i32 v3, v3, v6, v7
	v_max3_i32 v6, v52, v154, v177
	v_max3_i32 v7, v164, v48, v14
	v_max3_i32 v14, v155, v51, v176
	v_max3_i32 v15, v165, v15, v46
	v_max3_i32 v46, v50, v53, v175
	v_max3_i32 v48, v166, v162, v171
	v_max3_i32 v50, v157, v163, v174
	v_max3_i32 v18, v167, v18, v47
	v_max3_i32 v5, v5, v11, v173
	v_max3_i32 v11, v168, v160, v158
	v_max3_i32 v10, v13, v10, v172
	v_max3_i32 v13, v169, v153, v159
	v_max3_i32 v2, v4, v2, v9
	v_max3_i32 v4, v170, v8, v161
	v_max_i32_e32 v8, v12, v50
	v_min_i32_e32 v9, v12, v50
	v_max_i32_e32 v12, v3, v18
	v_min_i32_e32 v3, v3, v18
	v_max_i32_e32 v18, v6, v5
	v_min_i32_e32 v5, v6, v5
	v_max_i32_e32 v6, v7, v11
	v_min_i32_e32 v7, v7, v11
	v_max_i32_e32 v11, v14, v10
	v_min_i32_e32 v10, v14, v10
	v_max_i32_e32 v14, v15, v13
	v_min_i32_e32 v13, v15, v13
	v_max_i32_e32 v15, v46, v2
	v_min_i32_e32 v2, v46, v2
	v_max_i32_e32 v46, v48, v4
	v_min_i32_e32 v4, v48, v4
	v_max_i32_e32 v47, v8, v11
	v_min_i32_e32 v8, v8, v11
	v_max_i32_e32 v11, v12, v14
	v_min_i32_e32 v12, v12, v14
	v_max_i32_e32 v14, v18, v15
	v_min_i32_e32 v15, v18, v15
	v_max_i32_e32 v18, v6, v46
	v_min_i32_e32 v6, v6, v46
	v_max_i32_e32 v46, v9, v10
	v_min_i32_e32 v9, v9, v10
	v_max_i32_e32 v10, v3, v13
	v_min_i32_e32 v3, v3, v13
	v_max_i32_e32 v13, v5, v2
	v_min_i32_e32 v2, v5, v2
	v_max_i32_e32 v5, v7, v4
	v_min_i32_e32 v4, v7, v4
	v_max_i32_e32 v7, v47, v14
	v_min_i32_e32 v14, v47, v14
	v_max_i32_e32 v47, v11, v18
	v_min_i32_e32 v11, v11, v18
	v_max_i32_e32 v18, v8, v15
	v_min_i32_e32 v8, v8, v15
	v_max_i32_e32 v15, v12, v6
	v_min_i32_e32 v6, v12, v6
	v_max_i32_e32 v12, v46, v13
	v_min_i32_e32 v13, v46, v13
	v_max_i32_e32 v46, v10, v5
	v_min_i32_e32 v5, v10, v5
	v_max_i32_e32 v10, v9, v2
	v_min_i32_e32 v2, v9, v2
	v_max_i32_e32 v9, v3, v4
	v_min_i32_e32 v3, v3, v4
	v_max_i32_e32 v4, v7, v47
	v_min_i32_e32 v7, v7, v47
	v_max_i32_e32 v47, v14, v11
	v_min_i32_e32 v11, v14, v11
	v_max_i32_e32 v14, v18, v15
	v_min_i32_e32 v15, v18, v15
	v_max_i32_e32 v18, v8, v6
	v_min_i32_e32 v6, v8, v6
	v_max_i32_e32 v8, v12, v46
	v_min_i32_e32 v12, v12, v46
	v_max_i32_e32 v46, v13, v5
	v_min_i32_e32 v5, v13, v5
	v_max_i32_e32 v13, v10, v9
	v_min_i32_e32 v9, v10, v9
	v_max_i32_e32 v10, v2, v3
	v_min_i32_e32 v2, v2, v3
	ds_swizzle_b32 v3, v4 offset:swizzle(SWAP,16)
	ds_swizzle_b32 v48, v7 offset:swizzle(SWAP,16)
	ds_swizzle_b32 v50, v47 offset:swizzle(SWAP,16)
	ds_swizzle_b32 v51, v11 offset:swizzle(SWAP,16)
	ds_swizzle_b32 v52, v14 offset:swizzle(SWAP,16)
	ds_swizzle_b32 v53, v15 offset:swizzle(SWAP,16)
	ds_swizzle_b32 v153, v18 offset:swizzle(SWAP,16)
	ds_swizzle_b32 v154, v6 offset:swizzle(SWAP,16)
	ds_swizzle_b32 v155, v8 offset:swizzle(SWAP,16)
	ds_swizzle_b32 v156, v12 offset:swizzle(SWAP,16)
	ds_swizzle_b32 v157, v46 offset:swizzle(SWAP,16)
	ds_swizzle_b32 v158, v2 offset:swizzle(SWAP,16)
	ds_swizzle_b32 v159, v10 offset:swizzle(SWAP,16)
	ds_swizzle_b32 v160, v9 offset:swizzle(SWAP,16)
	ds_swizzle_b32 v161, v13 offset:swizzle(SWAP,16)
	ds_swizzle_b32 v162, v5 offset:swizzle(SWAP,16)
	s_waitcnt lgkmcnt(0)
; __device__ __forceinline__ void merge16p(int (&a)[16], const int (&b)[16]) {
; #pragma unroll
;   for (int i = 0; i < 16; ++i) a[i] = max(a[i], b[15 - i]);
; #pragma unroll
;   for (int j = 8; j > 0; j >>= 1)
; #pragma unroll
;     for (int i = 0; i < 16; ++i) {
;       int l = i ^ j;
;       if (l > i) { CE1(a[i], a[l]); }
;     }
; }
; __device__ __forceinline__ void xmerge16p(int (&a)[16], int mask) {
;   int b[16];
; #pragma unroll
;   for (int i = 0; i < 16; ++i) b[i] = (mask == 16) ? __builtin_amdgcn_ds_swizzle(a[i], 0x401F) : __shfl_xor(a[i], 32);
;   merge16p(a, b);
; }
	v_max_i32_e32 v4, v4, v158
	v_max_i32_e32 v7, v7, v159
	v_max_i32_e32 v47, v47, v160
	v_max_i32_e32 v11, v11, v161
	v_max_i32_e32 v14, v14, v162
	v_max_i32_e32 v15, v15, v157
	v_max_i32_e32 v18, v18, v156
	v_max_i32_e32 v6, v6, v155
	v_max_i32_e32 v8, v8, v154
	v_max_i32_e32 v12, v12, v153
	v_max_i32_e32 v46, v46, v53
	v_max_i32_e32 v5, v5, v52
	v_max_i32_e32 v13, v13, v51
	v_max_i32_e32 v9, v9, v50
	v_max_i32_e32 v10, v10, v48
	v_max_i32_e32 v2, v2, v3
	v_max_i32_e32 v3, v4, v8
	v_min_i32_e32 v4, v4, v8
	v_max_i32_e32 v8, v7, v12
	v_min_i32_e32 v7, v7, v12
	v_max_i32_e32 v12, v47, v46
	v_min_i32_e32 v46, v47, v46
	v_max_i32_e32 v47, v11, v5
	v_min_i32_e32 v5, v11, v5
	v_max_i32_e32 v11, v14, v13
	v_min_i32_e32 v13, v14, v13
	v_max_i32_e32 v14, v15, v9
	v_min_i32_e32 v9, v15, v9
	v_max_i32_e32 v15, v18, v10
	v_min_i32_e32 v10, v18, v10
	v_max_i32_e32 v18, v6, v2
	v_min_i32_e32 v2, v6, v2
	v_max_i32_e32 v6, v3, v11
	v_min_i32_e32 v3, v3, v11
	v_max_i32_e32 v11, v8, v14
	v_min_i32_e32 v8, v8, v14
	v_max_i32_e32 v14, v12, v15
	v_min_i32_e32 v12, v12, v15
	v_max_i32_e32 v15, v47, v18
	v_min_i32_e32 v18, v47, v18
	v_max_i32_e32 v47, v4, v13
	v_min_i32_e32 v4, v4, v13
	v_max_i32_e32 v13, v7, v9
	v_min_i32_e32 v7, v7, v9
	v_max_i32_e32 v9, v46, v10
	v_min_i32_e32 v10, v46, v10
	v_max_i32_e32 v46, v5, v2
	v_min_i32_e32 v2, v5, v2
	v_max_i32_e32 v5, v6, v14
	v_min_i32_e32 v6, v6, v14
	v_max_i32_e32 v14, v11, v15
	v_min_i32_e32 v11, v11, v15
	v_max_i32_e32 v15, v3, v12
	v_min_i32_e32 v3, v3, v12
	v_max_i32_e32 v12, v8, v18
	v_min_i32_e32 v8, v8, v18
	v_max_i32_e32 v18, v47, v9
	v_min_i32_e32 v9, v47, v9
	v_max_i32_e32 v47, v13, v46
	v_min_i32_e32 v13, v13, v46
	v_max_i32_e32 v46, v4, v10
	v_min_i32_e32 v4, v4, v10
	v_max_i32_e32 v10, v7, v2
	v_min_i32_e32 v2, v7, v2
	v_max_i32_e32 v7, v5, v14
	v_min_i32_e32 v5, v5, v14
	v_max_i32_e32 v14, v6, v11
	v_min_i32_e32 v6, v6, v11
	v_max_i32_e32 v11, v15, v12
	v_min_i32_e32 v12, v15, v12
	v_max_i32_e32 v15, v3, v8
	v_min_i32_e32 v3, v3, v8
	v_max_i32_e32 v8, v18, v47
	v_min_i32_e32 v18, v18, v47
	v_max_i32_e32 v47, v9, v13
	v_min_i32_e32 v9, v9, v13
	v_max_i32_e32 v13, v46, v10
	v_min_i32_e32 v10, v46, v10
	v_max_i32_e32 v46, v4, v2
	v_min_i32_e32 v2, v4, v2
	ds_bpermute_b32 v4, v54, v7
	ds_bpermute_b32 v48, v54, v5
	ds_bpermute_b32 v50, v54, v14
	ds_bpermute_b32 v51, v54, v6
	ds_bpermute_b32 v52, v54, v11
	ds_bpermute_b32 v53, v54, v12
	ds_bpermute_b32 v153, v54, v15
	ds_bpermute_b32 v154, v54, v3
	ds_bpermute_b32 v155, v54, v8
	ds_bpermute_b32 v156, v54, v18
	ds_bpermute_b32 v157, v54, v47
	ds_bpermute_b32 v158, v54, v2
	ds_bpermute_b32 v159, v54, v46
	ds_bpermute_b32 v160, v54, v10
	ds_bpermute_b32 v161, v54, v13
	ds_bpermute_b32 v162, v54, v9
	s_waitcnt lgkmcnt(4)
	v_max_i32_e32 v7, v7, v158
	s_waitcnt lgkmcnt(3)
	v_max_i32_e32 v5, v5, v159
	s_waitcnt lgkmcnt(2)
	v_max_i32_e32 v14, v14, v160
	s_waitcnt lgkmcnt(1)
	v_max_i32_e32 v6, v6, v161
	s_waitcnt lgkmcnt(0)
; __device__ __forceinline__ f32x4 mfma16(bf16x8 a, bf16x8 b, f32x4 c) { return __builtin_amdgcn_mfma_f32_16x16x32_bf16(a, b, c, 0, 0, 0); }
; __device__ __forceinline__ void merge16p(int (&a)[16], const int (&b)[16]) {
;     ...
;   for (int j = 8; j > 0; j >>= 1)
; #pragma unroll
;     for (int i = 0; i < 16; ++i) {
;       int l = i ^ j;
;       if (l > i) { CE1(a[i], a[l]); }
;     }
; }
; __device__ __forceinline__ void xmerge16p(int (&a)[16], int mask) {
;   int b[16];
; #pragma unroll
;   for (int i = 0; i < 16; ++i) b[i] = (mask == 16) ? __builtin_amdgcn_ds_swizzle(a[i], 0x401F) : __shfl_xor(a[i], 32);
;   merge16p(a, b);
; __device__ void ph_score(const P& p, int* lds) {
;     ...
;       for (int ks = 0; ks < 4; ++ks) {
;         bf16x8 qf = *(const bf16x8*)(Qb + tok * 2048 + h * 256 + half * 128 + ks * 32 + fq * 8);
; #pragma unroll
;         for (int mt = 0; mt < 8; ++mt) {
;           bf16x8 kf = *(const bf16x8*)(Kb + (mt * 16 + fr) * 128 + ks * 32 + fq * 8);
;           sc[mt] = mfma16(kf, qf, sc[mt]);
;     ...
;       int idx4[4];
; #pragma unroll
;       for (int i = 0; i < 16; ++i) {
;         const int k = key_unmap(a[i]);
;         tv[half][i] = __int_as_float(k & ~0x7f);
;         if ((i >> 2) == 0) idx4[i & 3] = k & 0x7f;
;       }
; #pragma unroll
;       for (int i = 4; i < 16; ++i) {
;         const int k = key_unmap(a[i]) & 0x7f;
;         if ((i >> 2) == 1) idx4[i & 3] = (fq == 1) ? k : idx4[i & 3];
;         if ((i >> 2) == 2) idx4[i & 3] = (fq == 2) ? k : idx4[i & 3];
;         if ((i >> 2) == 3) idx4[i & 3] = (fq == 3) ? k : idx4[i & 3];
;       }
;       *(int4*)(myl + half * 16 + fq * 4) = make_int4(idx4[0], idx4[1], idx4[2], idx4[3]);
	v_max_i32_e32 v11, v11, v162
	v_max_i32_e32 v12, v12, v157
	v_max_i32_e32 v15, v15, v156
	v_max_i32_e32 v3, v3, v155
	v_max_i32_e32 v8, v8, v154
	v_max_i32_e32 v18, v18, v153
	v_max_i32_e32 v47, v47, v53
	v_max_i32_e32 v9, v9, v52
	v_max_i32_e32 v13, v13, v51
	v_max_i32_e32 v10, v10, v50
	v_max_i32_e32 v46, v46, v48
	v_max_i32_e32 v2, v2, v4
	v_max_i32_e32 v4, v7, v8
	v_min_i32_e32 v7, v7, v8
	v_max_i32_e32 v8, v5, v18
	v_min_i32_e32 v5, v5, v18
	v_max_i32_e32 v18, v14, v47
	v_min_i32_e32 v14, v14, v47
	v_max_i32_e32 v47, v6, v9
	v_min_i32_e32 v6, v6, v9
	v_max_i32_e32 v9, v11, v13
	v_min_i32_e32 v11, v11, v13
	v_max_i32_e32 v13, v12, v10
	v_min_i32_e32 v10, v12, v10
	v_max_i32_e32 v12, v15, v46
	v_min_i32_e32 v15, v15, v46
	v_max_i32_e32 v46, v3, v2
	v_min_i32_e32 v2, v3, v2
	v_max_i32_e32 v3, v4, v9
	v_min_i32_e32 v4, v4, v9
	v_max_i32_e32 v9, v8, v13
	v_min_i32_e32 v8, v8, v13
	v_max_i32_e32 v13, v18, v12
	v_min_i32_e32 v12, v18, v12
	v_max_i32_e32 v18, v47, v46
	v_min_i32_e32 v46, v47, v46
	v_max_i32_e32 v47, v7, v11
	v_min_i32_e32 v7, v7, v11
	v_max_i32_e32 v11, v5, v10
	v_min_i32_e32 v5, v5, v10
	v_max_i32_e32 v10, v14, v15
	v_min_i32_e32 v14, v14, v15
	v_max_i32_e32 v15, v6, v2
	v_min_i32_e32 v2, v6, v2
	v_max_i32_e32 v6, v3, v13
	v_min_i32_e32 v3, v3, v13
	v_max_i32_e32 v13, v9, v18
	v_min_i32_e32 v9, v9, v18
	v_max_i32_e32 v48, v4, v12
	v_min_i32_e32 v4, v4, v12
	v_max_i32_e32 v12, v8, v46
	v_min_i32_e32 v8, v8, v46
	v_max_i32_e32 v50, v47, v10
	v_min_i32_e32 v10, v47, v10
	v_max_i32_e32 v47, v11, v15
	v_min_i32_e32 v11, v11, v15
	v_max_i32_e32 v15, v7, v14
	v_min_i32_e32 v7, v7, v14
	v_max_i32_e32 v14, v5, v2
	v_min_i32_e32 v2, v5, v2
	v_max_i32_e32 v5, v6, v13
	v_min_i32_e32 v6, v6, v13
	v_max_i32_e32 v13, v3, v9
	v_min_i32_e32 v3, v3, v9
	v_max_i32_e32 v18, v48, v12
	v_min_i32_e32 v155, v48, v12
	v_max_i32_e32 v52, v4, v8
	v_min_i32_e32 v46, v4, v8
	v_max_i32_e32 v159, v50, v47
	v_min_i32_e32 v156, v50, v47
	v_max_i32_e32 v53, v10, v11
	v_min_i32_e32 v47, v10, v11
	v_max_i32_e32 v160, v15, v14
	v_min_i32_e32 v158, v15, v14
	v_max_i32_e32 v154, v7, v2
	v_min_i32_e32 v51, v7, v2
	v_ashrrev_i32_e32 v2, 31, v5
	v_and_b32_e32 v4, 0x7fffffff, v2
	v_bitop3_b32 v161, v2, v5, s75 bitop3:0x6c
	v_bitop3_b32 v2, v4, s80, v5 bitop3:0x48
	v_ashrrev_i32_e32 v4, 31, v6
	v_and_b32_e32 v5, 0x7fffffff, v4
	v_bitop3_b32 v157, v4, v6, s75 bitop3:0x6c
	v_bitop3_b32 v4, v5, s80, v6 bitop3:0x48
	v_ashrrev_i32_e32 v5, 31, v13
	v_and_b32_e32 v6, 0x7fffffff, v5
	v_bitop3_b32 v153, v5, v13, s75 bitop3:0x6c
	v_bitop3_b32 v5, v6, s80, v13 bitop3:0x48
	v_ashrrev_i32_e32 v6, 31, v3
	v_and_b32_e32 v7, 0x7fffffff, v6
	v_bitop3_b32 v50, v6, v3, s75 bitop3:0x6c
	v_ashrrev_i32_e32 v6, 31, v18
	v_bitop3_b32 v6, v6, s80, v18 bitop3:0x48
	v_cndmask_b32_e64 v2, v2, v6, s[6:7]
	v_ashrrev_i32_e32 v6, 31, v155
	v_bitop3_b32 v6, v6, s80, v155 bitop3:0x48
	v_cndmask_b32_e64 v4, v4, v6, s[6:7]
	v_ashrrev_i32_e32 v6, 31, v52
	v_bitop3_b32 v6, v6, s80, v52 bitop3:0x48
	v_cndmask_b32_e64 v5, v5, v6, s[6:7]
	v_ashrrev_i32_e32 v6, 31, v46
	v_bitop3_b32 v3, v7, s80, v3 bitop3:0x48
	v_bitop3_b32 v6, v6, s80, v46 bitop3:0x48
	v_cndmask_b32_e64 v3, v3, v6, s[6:7]
	v_ashrrev_i32_e32 v6, 31, v159
	v_bitop3_b32 v6, v6, s80, v159 bitop3:0x48
	v_cndmask_b32_e64 v2, v2, v6, s[4:5]
	v_ashrrev_i32_e32 v6, 31, v156
	v_bitop3_b32 v6, v6, s80, v156 bitop3:0x48
	v_cndmask_b32_e64 v4, v4, v6, s[4:5]
	v_ashrrev_i32_e32 v6, 31, v53
	v_bitop3_b32 v6, v6, s80, v53 bitop3:0x48
	v_cndmask_b32_e64 v5, v5, v6, s[4:5]
	v_ashrrev_i32_e32 v6, 31, v47
	v_bitop3_b32 v6, v6, s80, v47 bitop3:0x48
	v_cndmask_b32_e64 v6, v3, v6, s[4:5]
	v_ashrrev_i32_e32 v3, 31, v160
	v_bitop3_b32 v3, v3, s80, v160 bitop3:0x48
	v_cndmask_b32_e64 v2, v2, v3, s[0:1]
	v_ashrrev_i32_e32 v3, 31, v158
	v_bitop3_b32 v3, v3, s80, v158 bitop3:0x48
	v_cndmask_b32_e64 v3, v4, v3, s[0:1]
	v_ashrrev_i32_e32 v4, 31, v154
	v_bitop3_b32 v4, v4, s80, v154 bitop3:0x48
	v_cndmask_b32_e64 v4, v5, v4, s[0:1]
	v_ashrrev_i32_e32 v5, 31, v51
	v_bitop3_b32 v5, v5, s80, v51 bitop3:0x48
	v_lshl_add_u64 v[14:15], v[24:25], 0, s[70:71]
	v_cndmask_b32_e64 v5, v6, v5, s[0:1]
	v_lshl_add_u64 v[190:191], v[14:15], 0, v[28:29]
	v_lshl_add_u64 v[10:11], v[14:15], 0, v[30:31]
	v_lshl_add_u64 v[162:163], v[14:15], 0, v[32:33]
	v_lshl_add_u64 v[166:167], v[14:15], 0, v[34:35]
	v_lshl_add_u64 v[170:171], v[14:15], 0, v[36:37]
	v_lshl_add_u64 v[174:175], v[14:15], 0, v[38:39]
	v_lshl_add_u64 v[178:179], v[14:15], 0, v[40:41]
	v_lshl_add_u64 v[182:183], v[14:15], 0, v[42:43]
	ds_write_b128 v150, v[2:5]
	global_load_dwordx4 v[2:5], v[0:1], off offset:256


; __device__ __forceinline__ f32x4 mfma16(bf16x8 a, bf16x8 b, f32x4 c) { return __builtin_amdgcn_mfma_f32_16x16x32_bf16(a, b, c, 0, 0, 0); }
; __device__ void ph_score(const P& p, int* lds) {
;     ...
;       for (int ks = 0; ks < 4; ++ks) {
;         bf16x8 qf = *(const bf16x8*)(Qb + tok * 2048 + h * 256 + half * 128 + ks * 32 + fq * 8);
; #pragma unroll
;         for (int mt = 0; mt < 8; ++mt) {
;           bf16x8 kf = *(const bf16x8*)(Kb + (mt * 16 + fr) * 128 + ks * 32 + fq * 8);
;           sc[mt] = mfma16(kf, qf, sc[mt]);
;         }
	ds_read_b128 v[6:9], v224 offset:0
	v_lshl_add_u64 v[192:193], v[14:15], 0, 64


; __device__ __forceinline__ f32x4 mfma16(bf16x8 a, bf16x8 b, f32x4 c) { return __builtin_amdgcn_mfma_f32_16x16x32_bf16(a, b, c, 0, 0, 0); }
; __device__ void ph_score(const P& p, int* lds) {
;     ...
;       for (int ks = 0; ks < 4; ++ks) {
;         bf16x8 qf = *(const bf16x8*)(Qb + tok * 2048 + h * 256 + half * 128 + ks * 32 + fq * 8);
; #pragma unroll
;         for (int mt = 0; mt < 8; ++mt) {
;           bf16x8 kf = *(const bf16x8*)(Kb + (mt * 16 + fr) * 128 + ks * 32 + fq * 8);
;           sc[mt] = mfma16(kf, qf, sc[mt]);
;         }
	ds_read_b128 v[10:13], v224 offset:4352
	v_lshl_add_u64 v[194:195], v[14:15], 0, s[76:77]


; __device__ __forceinline__ f32x4 mfma16(bf16x8 a, bf16x8 b, f32x4 c) { return __builtin_amdgcn_mfma_f32_16x16x32_bf16(a, b, c, 0, 0, 0); }
; __device__ void ph_score(const P& p, int* lds) {
;     ...
;       for (int ks = 0; ks < 4; ++ks) {
;         bf16x8 qf = *(const bf16x8*)(Qb + tok * 2048 + h * 256 + half * 128 + ks * 32 + fq * 8);
; #pragma unroll
;         for (int mt = 0; mt < 8; ++mt) {
;           bf16x8 kf = *(const bf16x8*)(Kb + (mt * 16 + fr) * 128 + ks * 32 + fq * 8);
;           sc[mt] = mfma16(kf, qf, sc[mt]);
;         }
	ds_read_b128 v[162:165], v224 offset:8704
	v_cmp_gt_i32_e64 s[26:27], 0, v18


; __device__ __forceinline__ f32x4 mfma16(bf16x8 a, bf16x8 b, f32x4 c) { return __builtin_amdgcn_mfma_f32_16x16x32_bf16(a, b, c, 0, 0, 0); }
; __device__ void ph_score(const P& p, int* lds) {
;     ...
;       for (int ks = 0; ks < 4; ++ks) {
;         bf16x8 qf = *(const bf16x8*)(Qb + tok * 2048 + h * 256 + half * 128 + ks * 32 + fq * 8);
; #pragma unroll
;         for (int mt = 0; mt < 8; ++mt) {
;           bf16x8 kf = *(const bf16x8*)(Kb + (mt * 16 + fr) * 128 + ks * 32 + fq * 8);
;           sc[mt] = mfma16(kf, qf, sc[mt]);
;         }
	ds_read_b128 v[166:169], v224 offset:13056
	v_cmp_gt_i32_e64 s[20:21], 0, v155


; __device__ __forceinline__ f32x4 mfma16(bf16x8 a, bf16x8 b, f32x4 c) { return __builtin_amdgcn_mfma_f32_16x16x32_bf16(a, b, c, 0, 0, 0); }
; __device__ void ph_score(const P& p, int* lds) {
;     ...
;       for (int ks = 0; ks < 4; ++ks) {
;         bf16x8 qf = *(const bf16x8*)(Qb + tok * 2048 + h * 256 + half * 128 + ks * 32 + fq * 8);
; #pragma unroll
;         for (int mt = 0; mt < 8; ++mt) {
;           bf16x8 kf = *(const bf16x8*)(Kb + (mt * 16 + fr) * 128 + ks * 32 + fq * 8);
;           sc[mt] = mfma16(kf, qf, sc[mt]);
;         }
	ds_read_b128 v[170:173], v224 offset:17408
	v_cmp_gt_i32_e64 s[14:15], 0, v52


; __device__ __forceinline__ f32x4 mfma16(bf16x8 a, bf16x8 b, f32x4 c) { return __builtin_amdgcn_mfma_f32_16x16x32_bf16(a, b, c, 0, 0, 0); }
; __device__ void ph_score(const P& p, int* lds) {
;     ...
;       for (int ks = 0; ks < 4; ++ks) {
;         bf16x8 qf = *(const bf16x8*)(Qb + tok * 2048 + h * 256 + half * 128 + ks * 32 + fq * 8);
; #pragma unroll
;         for (int mt = 0; mt < 8; ++mt) {
;           bf16x8 kf = *(const bf16x8*)(Kb + (mt * 16 + fr) * 128 + ks * 32 + fq * 8);
;           sc[mt] = mfma16(kf, qf, sc[mt]);
;         }
	ds_read_b128 v[174:177], v224 offset:21760
	v_cmp_gt_i32_e32 vcc, 0, v46


; __device__ __forceinline__ f32x4 mfma16(bf16x8 a, bf16x8 b, f32x4 c) { return __builtin_amdgcn_mfma_f32_16x16x32_bf16(a, b, c, 0, 0, 0); }
; __device__ void ph_score(const P& p, int* lds) {
;     ...
;       for (int ks = 0; ks < 4; ++ks) {
;         bf16x8 qf = *(const bf16x8*)(Qb + tok * 2048 + h * 256 + half * 128 + ks * 32 + fq * 8);
; #pragma unroll
;         for (int mt = 0; mt < 8; ++mt) {
;           bf16x8 kf = *(const bf16x8*)(Kb + (mt * 16 + fr) * 128 + ks * 32 + fq * 8);
;           sc[mt] = mfma16(kf, qf, sc[mt]);
;         }
	ds_read_b128 v[178:181], v224 offset:26112
	v_cmp_gt_i32_e64 s[28:29], 0, v159


; __device__ __forceinline__ f32x4 mfma16(bf16x8 a, bf16x8 b, f32x4 c) { return __builtin_amdgcn_mfma_f32_16x16x32_bf16(a, b, c, 0, 0, 0); }
; __device__ void ph_score(const P& p, int* lds) {
;     ...
;       for (int ks = 0; ks < 4; ++ks) {
;         bf16x8 qf = *(const bf16x8*)(Qb + tok * 2048 + h * 256 + half * 128 + ks * 32 + fq * 8);
; #pragma unroll
;         for (int mt = 0; mt < 8; ++mt) {
;           bf16x8 kf = *(const bf16x8*)(Kb + (mt * 16 + fr) * 128 + ks * 32 + fq * 8);
;           sc[mt] = mfma16(kf, qf, sc[mt]);
;         }
	ds_read_b128 v[182:185], v224 offset:30464
	v_cmp_gt_i32_e64 s[22:23], 0, v156
	v_cmp_gt_i32_e64 s[16:17], 0, v53
	v_cmp_gt_i32_e64 s[10:11], 0, v47
	v_cmp_gt_i32_e64 s[30:31], 0, v160
	v_cmp_gt_i32_e64 s[24:25], 0, v158
	v_cmp_gt_i32_e64 s[18:19], 0, v154
	v_cmp_gt_i32_e64 s[12:13], 0, v51
	s_waitcnt vmcnt(0) lgkmcnt(0)
	v_mfma_f32_16x16x32_bf16 v[162:165], v[162:165], v[2:5], 0


; __device__ __forceinline__ f32x4 mfma16(bf16x8 a, bf16x8 b, f32x4 c) { return __builtin_amdgcn_mfma_f32_16x16x32_bf16(a, b, c, 0, 0, 0); }
; __device__ void ph_score(const P& p, int* lds) {
;     ...
;       for (int ks = 0; ks < 4; ++ks) {
;         bf16x8 qf = *(const bf16x8*)(Qb + tok * 2048 + h * 256 + half * 128 + ks * 32 + fq * 8);
; #pragma unroll
;         for (int mt = 0; mt < 8; ++mt) {
;           bf16x8 kf = *(const bf16x8*)(Kb + (mt * 16 + fr) * 128 + ks * 32 + fq * 8);
;           sc[mt] = mfma16(kf, qf, sc[mt]);
;         }
	ds_read_b128 v[186:189], v224 offset:64
	v_mfma_f32_16x16x32_bf16 v[6:9], v[6:9], v[2:5], 0
	v_mfma_f32_16x16x32_bf16 v[10:13], v[10:13], v[2:5], 0
	s_waitcnt vmcnt(0) lgkmcnt(0)
	v_mfma_f32_16x16x32_bf16 v[166:169], v[166:169], v[2:5], 0
	s_waitcnt vmcnt(0) lgkmcnt(0)
	v_mfma_f32_16x16x32_bf16 v[170:173], v[170:173], v[2:5], 0
	s_waitcnt vmcnt(0) lgkmcnt(0)
	v_mfma_f32_16x16x32_bf16 v[174:177], v[174:177], v[2:5], 0
	s_waitcnt vmcnt(0) lgkmcnt(0)
	v_mfma_f32_16x16x32_bf16 v[178:181], v[178:181], v[2:5], 0
	s_waitcnt vmcnt(0) lgkmcnt(0)
	v_mfma_f32_16x16x32_bf16 v[2:5], v[182:185], v[2:5], 0
	global_load_dwordx4 v[182:185], v[0:1], off offset:320
	s_waitcnt vmcnt(0) lgkmcnt(0)
	v_mfma_f32_16x16x32_bf16 v[6:9], v[186:189], v[182:185], v[6:9]
	v_lshl_add_u64 v[186:187], v[192:193], 0, v[30:31]


; __device__ __forceinline__ f32x4 mfma16(bf16x8 a, bf16x8 b, f32x4 c) { return __builtin_amdgcn_mfma_f32_16x16x32_bf16(a, b, c, 0, 0, 0); }
; __device__ void ph_score(const P& p, int* lds) {
;     ...
;       for (int ks = 0; ks < 4; ++ks) {
;         bf16x8 qf = *(const bf16x8*)(Qb + tok * 2048 + h * 256 + half * 128 + ks * 32 + fq * 8);
; #pragma unroll
;         for (int mt = 0; mt < 8; ++mt) {
;           bf16x8 kf = *(const bf16x8*)(Kb + (mt * 16 + fr) * 128 + ks * 32 + fq * 8);
;           sc[mt] = mfma16(kf, qf, sc[mt]);
;         }
	ds_read_b128 v[186:189], v224 offset:4416
	s_waitcnt vmcnt(0) lgkmcnt(0)
	v_mfma_f32_16x16x32_bf16 v[10:13], v[186:189], v[182:185], v[10:13]
	v_lshl_add_u64 v[186:187], v[192:193], 0, v[32:33]


; __device__ __forceinline__ f32x4 mfma16(bf16x8 a, bf16x8 b, f32x4 c) { return __builtin_amdgcn_mfma_f32_16x16x32_bf16(a, b, c, 0, 0, 0); }
; __device__ void ph_score(const P& p, int* lds) {
;     ...
;       for (int ks = 0; ks < 4; ++ks) {
;         bf16x8 qf = *(const bf16x8*)(Qb + tok * 2048 + h * 256 + half * 128 + ks * 32 + fq * 8);
; #pragma unroll
;         for (int mt = 0; mt < 8; ++mt) {
;           bf16x8 kf = *(const bf16x8*)(Kb + (mt * 16 + fr) * 128 + ks * 32 + fq * 8);
;           sc[mt] = mfma16(kf, qf, sc[mt]);
;         }
	ds_read_b128 v[186:189], v224 offset:8768
	s_waitcnt vmcnt(0) lgkmcnt(0)
	v_mfma_f32_16x16x32_bf16 v[162:165], v[186:189], v[182:185], v[162:165]
	v_lshl_add_u64 v[186:187], v[192:193], 0, v[34:35]


; __device__ __forceinline__ f32x4 mfma16(bf16x8 a, bf16x8 b, f32x4 c) { return __builtin_amdgcn_mfma_f32_16x16x32_bf16(a, b, c, 0, 0, 0); }
; __device__ void ph_score(const P& p, int* lds) {
;     ...
;       for (int ks = 0; ks < 4; ++ks) {
;         bf16x8 qf = *(const bf16x8*)(Qb + tok * 2048 + h * 256 + half * 128 + ks * 32 + fq * 8);
; #pragma unroll
;         for (int mt = 0; mt < 8; ++mt) {
;           bf16x8 kf = *(const bf16x8*)(Kb + (mt * 16 + fr) * 128 + ks * 32 + fq * 8);
;           sc[mt] = mfma16(kf, qf, sc[mt]);
;         }
	ds_read_b128 v[186:189], v224 offset:13120
	s_waitcnt vmcnt(0) lgkmcnt(0)
	v_mfma_f32_16x16x32_bf16 v[166:169], v[186:189], v[182:185], v[166:169]
	v_lshl_add_u64 v[186:187], v[192:193], 0, v[36:37]


; __device__ __forceinline__ f32x4 mfma16(bf16x8 a, bf16x8 b, f32x4 c) { return __builtin_amdgcn_mfma_f32_16x16x32_bf16(a, b, c, 0, 0, 0); }
; __device__ void ph_score(const P& p, int* lds) {
;     ...
;       for (int ks = 0; ks < 4; ++ks) {
;         bf16x8 qf = *(const bf16x8*)(Qb + tok * 2048 + h * 256 + half * 128 + ks * 32 + fq * 8);
; #pragma unroll
;         for (int mt = 0; mt < 8; ++mt) {
;           bf16x8 kf = *(const bf16x8*)(Kb + (mt * 16 + fr) * 128 + ks * 32 + fq * 8);
;           sc[mt] = mfma16(kf, qf, sc[mt]);
;         }
	ds_read_b128 v[186:189], v224 offset:17472
	s_waitcnt vmcnt(0) lgkmcnt(0)
	v_mfma_f32_16x16x32_bf16 v[170:173], v[186:189], v[182:185], v[170:173]
	v_lshl_add_u64 v[186:187], v[192:193], 0, v[38:39]


; __device__ __forceinline__ f32x4 mfma16(bf16x8 a, bf16x8 b, f32x4 c) { return __builtin_amdgcn_mfma_f32_16x16x32_bf16(a, b, c, 0, 0, 0); }
; __device__ void ph_score(const P& p, int* lds) {
;     ...
;       for (int ks = 0; ks < 4; ++ks) {
;         bf16x8 qf = *(const bf16x8*)(Qb + tok * 2048 + h * 256 + half * 128 + ks * 32 + fq * 8);
; #pragma unroll
;         for (int mt = 0; mt < 8; ++mt) {
;           bf16x8 kf = *(const bf16x8*)(Kb + (mt * 16 + fr) * 128 + ks * 32 + fq * 8);
;           sc[mt] = mfma16(kf, qf, sc[mt]);
;         }
	ds_read_b128 v[186:189], v224 offset:21824
	s_waitcnt vmcnt(0) lgkmcnt(0)
	v_mfma_f32_16x16x32_bf16 v[174:177], v[186:189], v[182:185], v[174:177]
	v_lshl_add_u64 v[186:187], v[192:193], 0, v[40:41]


; __device__ __forceinline__ f32x4 mfma16(bf16x8 a, bf16x8 b, f32x4 c) { return __builtin_amdgcn_mfma_f32_16x16x32_bf16(a, b, c, 0, 0, 0); }
; __device__ void ph_score(const P& p, int* lds) {
;     ...
;       for (int ks = 0; ks < 4; ++ks) {
;         bf16x8 qf = *(const bf16x8*)(Qb + tok * 2048 + h * 256 + half * 128 + ks * 32 + fq * 8);
; #pragma unroll
;         for (int mt = 0; mt < 8; ++mt) {
;           bf16x8 kf = *(const bf16x8*)(Kb + (mt * 16 + fr) * 128 + ks * 32 + fq * 8);
;           sc[mt] = mfma16(kf, qf, sc[mt]);
;         }
	ds_read_b128 v[186:189], v224 offset:26176
	s_waitcnt vmcnt(0) lgkmcnt(0)
	v_mfma_f32_16x16x32_bf16 v[178:181], v[186:189], v[182:185], v[178:181]
	v_lshl_add_u64 v[186:187], v[192:193], 0, v[42:43]


; __device__ __forceinline__ f32x4 mfma16(bf16x8 a, bf16x8 b, f32x4 c) { return __builtin_amdgcn_mfma_f32_16x16x32_bf16(a, b, c, 0, 0, 0); }
; __device__ void ph_score(const P& p, int* lds) {
;     ...
;       for (int ks = 0; ks < 4; ++ks) {
;         bf16x8 qf = *(const bf16x8*)(Qb + tok * 2048 + h * 256 + half * 128 + ks * 32 + fq * 8);
; #pragma unroll
;         for (int mt = 0; mt < 8; ++mt) {
;           bf16x8 kf = *(const bf16x8*)(Kb + (mt * 16 + fr) * 128 + ks * 32 + fq * 8);
;           sc[mt] = mfma16(kf, qf, sc[mt]);
;         }
	ds_read_b128 v[186:189], v224 offset:30528
	v_lshl_add_u64 v[192:193], v[14:15], 0, s[72:73]
	s_waitcnt vmcnt(0) lgkmcnt(0)
	v_mfma_f32_16x16x32_bf16 v[2:5], v[186:189], v[182:185], v[2:5]
	global_load_dwordx4 v[182:185], v[0:1], off offset:384


; __device__ __forceinline__ f32x4 mfma16(bf16x8 a, bf16x8 b, f32x4 c) { return __builtin_amdgcn_mfma_f32_16x16x32_bf16(a, b, c, 0, 0, 0); }
; __device__ void ph_score(const P& p, int* lds) {
;     ...
;       for (int ks = 0; ks < 4; ++ks) {
;         bf16x8 qf = *(const bf16x8*)(Qb + tok * 2048 + h * 256 + half * 128 + ks * 32 + fq * 8);
; #pragma unroll
;         for (int mt = 0; mt < 8; ++mt) {
;           bf16x8 kf = *(const bf16x8*)(Kb + (mt * 16 + fr) * 128 + ks * 32 + fq * 8);
;           sc[mt] = mfma16(kf, qf, sc[mt]);
;         }
	ds_read_b128 v[186:189], v224 offset:128
	s_waitcnt vmcnt(0) lgkmcnt(0)
	v_mfma_f32_16x16x32_bf16 v[6:9], v[186:189], v[182:185], v[6:9]
	v_lshl_add_u64 v[186:187], v[192:193], 0, v[30:31]


; __device__ __forceinline__ f32x4 mfma16(bf16x8 a, bf16x8 b, f32x4 c) { return __builtin_amdgcn_mfma_f32_16x16x32_bf16(a, b, c, 0, 0, 0); }
; __device__ void ph_score(const P& p, int* lds) {
;     ...
;       for (int ks = 0; ks < 4; ++ks) {
;         bf16x8 qf = *(const bf16x8*)(Qb + tok * 2048 + h * 256 + half * 128 + ks * 32 + fq * 8);
; #pragma unroll
;         for (int mt = 0; mt < 8; ++mt) {
;           bf16x8 kf = *(const bf16x8*)(Kb + (mt * 16 + fr) * 128 + ks * 32 + fq * 8);
;           sc[mt] = mfma16(kf, qf, sc[mt]);
;         }
	ds_read_b128 v[186:189], v224 offset:4480
	s_waitcnt vmcnt(0) lgkmcnt(0)
	v_mfma_f32_16x16x32_bf16 v[10:13], v[186:189], v[182:185], v[10:13]
	v_lshl_add_u64 v[186:187], v[192:193], 0, v[32:33]


; __device__ __forceinline__ f32x4 mfma16(bf16x8 a, bf16x8 b, f32x4 c) { return __builtin_amdgcn_mfma_f32_16x16x32_bf16(a, b, c, 0, 0, 0); }
; __device__ void ph_score(const P& p, int* lds) {
;     ...
;       for (int ks = 0; ks < 4; ++ks) {
;         bf16x8 qf = *(const bf16x8*)(Qb + tok * 2048 + h * 256 + half * 128 + ks * 32 + fq * 8);
; #pragma unroll
;         for (int mt = 0; mt < 8; ++mt) {
;           bf16x8 kf = *(const bf16x8*)(Kb + (mt * 16 + fr) * 128 + ks * 32 + fq * 8);
;           sc[mt] = mfma16(kf, qf, sc[mt]);
;         }
	ds_read_b128 v[186:189], v224 offset:8832
	s_waitcnt vmcnt(0) lgkmcnt(0)
	v_mfma_f32_16x16x32_bf16 v[162:165], v[186:189], v[182:185], v[162:165]
	v_lshl_add_u64 v[186:187], v[192:193], 0, v[34:35]


; __device__ __forceinline__ f32x4 mfma16(bf16x8 a, bf16x8 b, f32x4 c) { return __builtin_amdgcn_mfma_f32_16x16x32_bf16(a, b, c, 0, 0, 0); }
; __device__ void ph_score(const P& p, int* lds) {
;     ...
;       for (int ks = 0; ks < 4; ++ks) {
;         bf16x8 qf = *(const bf16x8*)(Qb + tok * 2048 + h * 256 + half * 128 + ks * 32 + fq * 8);
; #pragma unroll
;         for (int mt = 0; mt < 8; ++mt) {
;           bf16x8 kf = *(const bf16x8*)(Kb + (mt * 16 + fr) * 128 + ks * 32 + fq * 8);
;           sc[mt] = mfma16(kf, qf, sc[mt]);
;         }
	ds_read_b128 v[186:189], v224 offset:13184
	s_waitcnt vmcnt(0) lgkmcnt(0)
	v_mfma_f32_16x16x32_bf16 v[166:169], v[186:189], v[182:185], v[166:169]
	v_lshl_add_u64 v[186:187], v[192:193], 0, v[36:37]


; __device__ __forceinline__ f32x4 mfma16(bf16x8 a, bf16x8 b, f32x4 c) { return __builtin_amdgcn_mfma_f32_16x16x32_bf16(a, b, c, 0, 0, 0); }
; __device__ void ph_score(const P& p, int* lds) {
;     ...
;       for (int ks = 0; ks < 4; ++ks) {
;         bf16x8 qf = *(const bf16x8*)(Qb + tok * 2048 + h * 256 + half * 128 + ks * 32 + fq * 8);
; #pragma unroll
;         for (int mt = 0; mt < 8; ++mt) {
;           bf16x8 kf = *(const bf16x8*)(Kb + (mt * 16 + fr) * 128 + ks * 32 + fq * 8);
;           sc[mt] = mfma16(kf, qf, sc[mt]);
;         }
	ds_read_b128 v[186:189], v224 offset:17536
	s_waitcnt vmcnt(0) lgkmcnt(0)
	v_mfma_f32_16x16x32_bf16 v[170:173], v[186:189], v[182:185], v[170:173]
	v_lshl_add_u64 v[186:187], v[192:193], 0, v[38:39]


; __device__ __forceinline__ f32x4 mfma16(bf16x8 a, bf16x8 b, f32x4 c) { return __builtin_amdgcn_mfma_f32_16x16x32_bf16(a, b, c, 0, 0, 0); }
; __device__ void ph_score(const P& p, int* lds) {
;     ...
;       for (int ks = 0; ks < 4; ++ks) {
;         bf16x8 qf = *(const bf16x8*)(Qb + tok * 2048 + h * 256 + half * 128 + ks * 32 + fq * 8);
; #pragma unroll
;         for (int mt = 0; mt < 8; ++mt) {
;           bf16x8 kf = *(const bf16x8*)(Kb + (mt * 16 + fr) * 128 + ks * 32 + fq * 8);
;           sc[mt] = mfma16(kf, qf, sc[mt]);
;         }
	ds_read_b128 v[186:189], v224 offset:21888
	s_waitcnt vmcnt(0) lgkmcnt(0)
	v_mfma_f32_16x16x32_bf16 v[174:177], v[186:189], v[182:185], v[174:177]
	v_lshl_add_u64 v[186:187], v[192:193], 0, v[40:41]


; __device__ __forceinline__ f32x4 mfma16(bf16x8 a, bf16x8 b, f32x4 c) { return __builtin_amdgcn_mfma_f32_16x16x32_bf16(a, b, c, 0, 0, 0); }
; __device__ void ph_score(const P& p, int* lds) {
;     ...
;       for (int ks = 0; ks < 4; ++ks) {
;         bf16x8 qf = *(const bf16x8*)(Qb + tok * 2048 + h * 256 + half * 128 + ks * 32 + fq * 8);
; #pragma unroll
;         for (int mt = 0; mt < 8; ++mt) {
;           bf16x8 kf = *(const bf16x8*)(Kb + (mt * 16 + fr) * 128 + ks * 32 + fq * 8);
;           sc[mt] = mfma16(kf, qf, sc[mt]);
;         }
	ds_read_b128 v[186:189], v224 offset:26240
	s_waitcnt vmcnt(0) lgkmcnt(0)
	v_mfma_f32_16x16x32_bf16 v[178:181], v[186:189], v[182:185], v[178:181]
	v_lshl_add_u64 v[186:187], v[192:193], 0, v[42:43]


; __device__ __forceinline__ f32x4 mfma16(bf16x8 a, bf16x8 b, f32x4 c) { return __builtin_amdgcn_mfma_f32_16x16x32_bf16(a, b, c, 0, 0, 0); }
; __device__ void ph_score(const P& p, int* lds) {
;     ...
;       for (int ks = 0; ks < 4; ++ks) {
;         bf16x8 qf = *(const bf16x8*)(Qb + tok * 2048 + h * 256 + half * 128 + ks * 32 + fq * 8);
; #pragma unroll
;         for (int mt = 0; mt < 8; ++mt) {
;           bf16x8 kf = *(const bf16x8*)(Kb + (mt * 16 + fr) * 128 + ks * 32 + fq * 8);
;           sc[mt] = mfma16(kf, qf, sc[mt]);
;         }
	ds_read_b128 v[186:189], v224 offset:30592
	s_waitcnt vmcnt(0) lgkmcnt(0)
	v_mfma_f32_16x16x32_bf16 v[182:185], v[186:189], v[182:185], v[2:5]
	global_load_dwordx4 v[186:189], v[0:1], off offset:448
	s_nop 1


; __device__ __forceinline__ f32x4 mfma16(bf16x8 a, bf16x8 b, f32x4 c) { return __builtin_amdgcn_mfma_f32_16x16x32_bf16(a, b, c, 0, 0, 0); }
; __device__ void ph_score(const P& p, int* lds) {
;     ...
;       for (int ks = 0; ks < 4; ++ks) {
;         bf16x8 qf = *(const bf16x8*)(Qb + tok * 2048 + h * 256 + half * 128 + ks * 32 + fq * 8);
; #pragma unroll
;         for (int mt = 0; mt < 8; ++mt) {
;           bf16x8 kf = *(const bf16x8*)(Kb + (mt * 16 + fr) * 128 + ks * 32 + fq * 8);
;           sc[mt] = mfma16(kf, qf, sc[mt]);
;         }
;     ...
;           a[mt * 4 + r] = key_pack(sc[mt][r], mt * 16 + fq * 4 + r, 0x7f);
	ds_read_b128 v[0:3], v224 offset:192
	s_waitcnt vmcnt(0) lgkmcnt(0)
	v_mfma_f32_16x16x32_bf16 v[190:193], v[0:3], v[186:189], v[6:9]
	v_lshl_add_u64 v[0:1], v[194:195], 0, v[30:31]
	s_nop 0
	s_nop 0
	s_nop 0
	ds_read_b128 v[0:3], v224 offset:4544
	s_nop 0
	v_lshl_add_u64 v[8:9], v[194:195], 0, v[36:37]
	s_nop 3
	v_and_b32_e32 v48, 0xffffff80, v190
	s_waitcnt vmcnt(0) lgkmcnt(0)
	v_mfma_f32_16x16x32_bf16 v[12:15], v[0:3], v[186:189], v[10:13]
	v_lshl_add_u64 v[0:1], v[194:195], 0, v[32:33]


; __device__ __forceinline__ f32x4 mfma16(bf16x8 a, bf16x8 b, f32x4 c) { return __builtin_amdgcn_mfma_f32_16x16x32_bf16(a, b, c, 0, 0, 0); }
; __device__ void ph_score(const P& p, int* lds) {
;     ...
;       for (int ks = 0; ks < 4; ++ks) {
;         bf16x8 qf = *(const bf16x8*)(Qb + tok * 2048 + h * 256 + half * 128 + ks * 32 + fq * 8);
; #pragma unroll
;         for (int mt = 0; mt < 8; ++mt) {
;           bf16x8 kf = *(const bf16x8*)(Kb + (mt * 16 + fr) * 128 + ks * 32 + fq * 8);
;           sc[mt] = mfma16(kf, qf, sc[mt]);
;         }
	ds_read_b128 v[0:3], v224 offset:8896
	s_nop 0


; __device__ __forceinline__ f32x4 mfma16(bf16x8 a, bf16x8 b, f32x4 c) { return __builtin_amdgcn_mfma_f32_16x16x32_bf16(a, b, c, 0, 0, 0); }
; __device__ void ph_score(const P& p, int* lds) {
;     ...
;       for (int ks = 0; ks < 4; ++ks) {
;         bf16x8 qf = *(const bf16x8*)(Qb + tok * 2048 + h * 256 + half * 128 + ks * 32 + fq * 8);
; #pragma unroll
;         for (int mt = 0; mt < 8; ++mt) {
;           bf16x8 kf = *(const bf16x8*)(Kb + (mt * 16 + fr) * 128 + ks * 32 + fq * 8);
;           sc[mt] = mfma16(kf, qf, sc[mt]);
;         }
	ds_read_b128 v[8:11], v224 offset:17600
	s_waitcnt vmcnt(0) lgkmcnt(0)
	v_mfma_f32_16x16x32_bf16 v[4:7], v[0:3], v[186:189], v[162:165]
	v_lshl_add_u64 v[0:1], v[194:195], 0, v[34:35]


; __device__ __forceinline__ f32x4 mfma16(bf16x8 a, bf16x8 b, f32x4 c) { return __builtin_amdgcn_mfma_f32_16x16x32_bf16(a, b, c, 0, 0, 0); }
; __device__ void ph_score(const P& p, int* lds) {
;     ...
;       for (int ks = 0; ks < 4; ++ks) {
;         bf16x8 qf = *(const bf16x8*)(Qb + tok * 2048 + h * 256 + half * 128 + ks * 32 + fq * 8);
; #pragma unroll
;         for (int mt = 0; mt < 8; ++mt) {
;           bf16x8 kf = *(const bf16x8*)(Kb + (mt * 16 + fr) * 128 + ks * 32 + fq * 8);
;           sc[mt] = mfma16(kf, qf, sc[mt]);
;         }
	ds_read_b128 v[0:3], v224 offset:13248
	s_waitcnt vmcnt(0) lgkmcnt(0)
	v_mfma_f32_16x16x32_bf16 v[162:165], v[8:11], v[186:189], v[170:173]
	v_lshl_add_u64 v[8:9], v[194:195], 0, v[38:39]


; __device__ __forceinline__ f32x4 mfma16(bf16x8 a, bf16x8 b, f32x4 c) { return __builtin_amdgcn_mfma_f32_16x16x32_bf16(a, b, c, 0, 0, 0); }
; __device__ void ph_score(const P& p, int* lds) {
;     ...
;       for (int ks = 0; ks < 4; ++ks) {
;         bf16x8 qf = *(const bf16x8*)(Qb + tok * 2048 + h * 256 + half * 128 + ks * 32 + fq * 8);
; #pragma unroll
;         for (int mt = 0; mt < 8; ++mt) {
;           bf16x8 kf = *(const bf16x8*)(Kb + (mt * 16 + fr) * 128 + ks * 32 + fq * 8);
;           sc[mt] = mfma16(kf, qf, sc[mt]);
;         }
	ds_read_b128 v[8:11], v224 offset:21952
	s_waitcnt vmcnt(0) lgkmcnt(0)
	v_mfma_f32_16x16x32_bf16 v[0:3], v[0:3], v[186:189], v[166:169]
	v_lshl_add_u64 v[170:171], v[194:195], 0, v[42:43]


; __device__ __forceinline__ f32x4 mfma16(bf16x8 a, bf16x8 b, f32x4 c) { return __builtin_amdgcn_mfma_f32_16x16x32_bf16(a, b, c, 0, 0, 0); }
; __device__ void ph_score(const P& p, int* lds) {
;     ...
;       for (int ks = 0; ks < 4; ++ks) {
;         bf16x8 qf = *(const bf16x8*)(Qb + tok * 2048 + h * 256 + half * 128 + ks * 32 + fq * 8);
; #pragma unroll
;         for (int mt = 0; mt < 8; ++mt) {
;           bf16x8 kf = *(const bf16x8*)(Kb + (mt * 16 + fr) * 128 + ks * 32 + fq * 8);
;           sc[mt] = mfma16(kf, qf, sc[mt]);
;         }
	s_nop 0
	ds_read_b128 v[170:173], v224 offset:30656
	s_waitcnt vmcnt(0) lgkmcnt(0)
	v_mfma_f32_16x16x32_bf16 v[166:169], v[8:11], v[186:189], v[174:177]
	v_lshl_add_u64 v[8:9], v[194:195], 0, v[40:41]


; __device__ __forceinline__ int key_pack(float v, int payload, int mask) {
;   int b = (__float_as_int(v) & ~mask) | payload;
;   return b ^ ((b >> 31) & 0x7fffffff);
; }
; __device__ void ph_score(const P& p, int* lds) {
;     ...
;       int a[16], b[16];
; #pragma unroll
;       for (int mt = 0; mt < 4; ++mt)
; #pragma unroll
;         for (int r = 0; r < 4; ++r) {
;           a[mt * 4 + r] = key_pack(sc[mt][r], mt * 16 + fq * 4 + r, 0x7f);
;           b[mt * 4 + r] = key_pack(sc[mt + 4][r], (mt + 4) * 16 + fq * 4 + r, 0x7f);
;         }
;       sort16p(a);
	ds_read_b128 v[8:11], v224 offset:26304
	s_nop 0
	v_ashrrev_i32_e32 v174, 31, v190
	v_and_b32_e32 v174, 0x7fffffff, v174
	v_bitop3_b32 v48, v48, v174, v20 bitop3:0x36
	v_and_b32_e32 v174, 0xffffff80, v162
	v_ashrrev_i32_e32 v162, 31, v162
	v_and_b32_e32 v162, 0x7fffffff, v162
	v_ashrrev_i32_e32 v175, 31, v191
	v_bitop3_b32 v162, v174, v162, v56 bitop3:0x36
	v_and_b32_e32 v174, 0xffffff80, v191
	v_and_b32_e32 v175, 0x7fffffff, v175
	v_bitop3_b32 v174, v174, v175, v57 bitop3:0x36
	v_and_b32_e32 v175, 0xffffff80, v163
	v_ashrrev_i32_e32 v163, 31, v163
	v_and_b32_e32 v163, 0x7fffffff, v163
	v_ashrrev_i32_e32 v176, 31, v192
	v_bitop3_b32 v163, v175, v163, v58 bitop3:0x36
	v_and_b32_e32 v175, 0xffffff80, v192
	v_and_b32_e32 v176, 0x7fffffff, v176
	v_bitop3_b32 v175, v175, v176, v59 bitop3:0x36
	v_and_b32_e32 v176, 0xffffff80, v164
	v_ashrrev_i32_e32 v164, 31, v164
	v_and_b32_e32 v164, 0x7fffffff, v164
	v_ashrrev_i32_e32 v177, 31, v193
	v_bitop3_b32 v164, v176, v164, v60 bitop3:0x36
	v_and_b32_e32 v176, 0xffffff80, v193
	v_and_b32_e32 v177, 0x7fffffff, v177
	v_bitop3_b32 v176, v176, v177, v61 bitop3:0x36
	v_and_b32_e32 v177, 0xffffff80, v165
	v_ashrrev_i32_e32 v165, 31, v165
	v_and_b32_e32 v165, 0x7fffffff, v165
	v_bitop3_b32 v165, v177, v165, v62 bitop3:0x36
	v_and_b32_e32 v177, 0xffffff80, v12
	v_ashrrev_i32_e32 v12, 31, v12
	v_and_b32_e32 v12, 0x7fffffff, v12
	v_bitop3_b32 v12, v177, v12, v63 bitop3:0x36
	v_and_b32_e32 v177, 0xffffff80, v166
	v_ashrrev_i32_e32 v166, 31, v166
	v_and_b32_e32 v166, 0x7fffffff, v166
	v_bitop3_b32 v166, v177, v166, v64 bitop3:0x36
	v_and_b32_e32 v177, 0xffffff80, v13
	v_ashrrev_i32_e32 v13, 31, v13
	v_and_b32_e32 v13, 0x7fffffff, v13
	v_bitop3_b32 v13, v177, v13, v65 bitop3:0x36
	v_and_b32_e32 v177, 0xffffff80, v167
	v_ashrrev_i32_e32 v167, 31, v167
	v_and_b32_e32 v167, 0x7fffffff, v167
	v_bitop3_b32 v167, v177, v167, v66 bitop3:0x36
	v_and_b32_e32 v177, 0xffffff80, v14
	v_ashrrev_i32_e32 v14, 31, v14
	v_and_b32_e32 v14, 0x7fffffff, v14
	v_bitop3_b32 v14, v177, v14, v67 bitop3:0x36
	v_and_b32_e32 v177, 0xffffff80, v168
	v_ashrrev_i32_e32 v168, 31, v168
	v_and_b32_e32 v168, 0x7fffffff, v168
	v_bitop3_b32 v168, v177, v168, v68 bitop3:0x36
	v_and_b32_e32 v177, 0xffffff80, v15
	v_ashrrev_i32_e32 v15, 31, v15
	v_and_b32_e32 v15, 0x7fffffff, v15
	s_waitcnt vmcnt(0) lgkmcnt(0)
	v_mfma_f32_16x16x32_bf16 v[8:11], v[8:11], v[186:189], v[178:181]
	v_bitop3_b32 v15, v177, v15, v69 bitop3:0x36
	v_and_b32_e32 v177, 0xffffff80, v169
	v_ashrrev_i32_e32 v169, 31, v169
	v_and_b32_e32 v169, 0x7fffffff, v169
	v_bitop3_b32 v169, v177, v169, v70 bitop3:0x36
	v_and_b32_e32 v177, 0xffffff80, v4
	v_ashrrev_i32_e32 v4, 31, v4
	v_and_b32_e32 v4, 0x7fffffff, v4
	v_bitop3_b32 v4, v177, v4, v71 bitop3:0x36
	v_and_b32_e32 v177, 0xffffff80, v8
	v_ashrrev_i32_e32 v8, 31, v8
	v_and_b32_e32 v8, 0x7fffffff, v8
	v_bitop3_b32 v8, v177, v8, v72 bitop3:0x36
	v_and_b32_e32 v177, 0xffffff80, v5
	v_ashrrev_i32_e32 v5, 31, v5
	v_and_b32_e32 v5, 0x7fffffff, v5
	v_bitop3_b32 v5, v177, v5, v73 bitop3:0x36
	v_and_b32_e32 v177, 0xffffff80, v9
	v_ashrrev_i32_e32 v9, 31, v9
	v_and_b32_e32 v9, 0x7fffffff, v9
	v_bitop3_b32 v9, v177, v9, v74 bitop3:0x36
	v_and_b32_e32 v177, 0xffffff80, v6
	v_ashrrev_i32_e32 v6, 31, v6
	v_and_b32_e32 v6, 0x7fffffff, v6
	v_bitop3_b32 v6, v177, v6, v75 bitop3:0x36
	v_and_b32_e32 v177, 0xffffff80, v10
	v_ashrrev_i32_e32 v10, 31, v10
	v_and_b32_e32 v10, 0x7fffffff, v10
	v_bitop3_b32 v10, v177, v10, v76 bitop3:0x36
	v_and_b32_e32 v177, 0xffffff80, v7
	v_ashrrev_i32_e32 v7, 31, v7
	v_and_b32_e32 v7, 0x7fffffff, v7
	v_mfma_f32_16x16x32_bf16 v[170:173], v[170:173], v[186:189], v[182:185]
	v_bitop3_b32 v7, v177, v7, v77 bitop3:0x36
	v_and_b32_e32 v177, 0xffffff80, v11
	v_ashrrev_i32_e32 v11, 31, v11
	v_and_b32_e32 v11, 0x7fffffff, v11
	v_bitop3_b32 v11, v177, v11, v78 bitop3:0x36
	v_and_b32_e32 v177, 0xffffff80, v0
	v_ashrrev_i32_e32 v0, 31, v0
	v_and_b32_e32 v0, 0x7fffffff, v0
	v_bitop3_b32 v0, v177, v0, v79 bitop3:0x36
	v_and_b32_e32 v177, 0xffffff80, v170
	v_ashrrev_i32_e32 v170, 31, v170
	v_and_b32_e32 v170, 0x7fffffff, v170
	v_bitop3_b32 v170, v177, v170, v80 bitop3:0x36
	v_and_b32_e32 v177, 0xffffff80, v1
	v_ashrrev_i32_e32 v1, 31, v1
	v_and_b32_e32 v1, 0x7fffffff, v1
	v_bitop3_b32 v1, v177, v1, v81 bitop3:0x36
	v_and_b32_e32 v177, 0xffffff80, v171
	v_ashrrev_i32_e32 v171, 31, v171
	v_and_b32_e32 v171, 0x7fffffff, v171
	v_bitop3_b32 v171, v177, v171, v82 bitop3:0x36
	v_and_b32_e32 v177, 0xffffff80, v2
	v_ashrrev_i32_e32 v2, 31, v2
	v_and_b32_e32 v2, 0x7fffffff, v2
	v_bitop3_b32 v2, v177, v2, v83 bitop3:0x36
	v_and_b32_e32 v177, 0xffffff80, v172
	v_ashrrev_i32_e32 v172, 31, v172
	v_and_b32_e32 v172, 0x7fffffff, v172
	v_bitop3_b32 v172, v177, v172, v84 bitop3:0x36
	v_and_b32_e32 v177, 0xffffff80, v3
	v_ashrrev_i32_e32 v3, 31, v3
	v_and_b32_e32 v3, 0x7fffffff, v3
	v_bitop3_b32 v3, v177, v3, v85 bitop3:0x36
	v_and_b32_e32 v177, 0xffffff80, v173
	v_ashrrev_i32_e32 v173, 31, v173
	v_and_b32_e32 v173, 0x7fffffff, v173
	v_bitop3_b32 v173, v177, v173, v86 bitop3:0x36
	v_max_i32_e32 v177, v48, v174
	v_min_i32_e32 v48, v48, v174
	v_max_i32_e32 v174, v176, v175
	v_min_i32_e32 v175, v176, v175
	v_max_i32_e32 v176, v12, v13
	v_min_i32_e32 v12, v12, v13
	v_max_i32_e32 v13, v15, v14
	v_min_i32_e32 v14, v15, v14
	v_max_i32_e32 v15, v4, v5
	v_min_i32_e32 v4, v4, v5
	v_max_i32_e32 v5, v7, v6
	v_min_i32_e32 v6, v7, v6
	v_max_i32_e32 v7, v0, v1
	v_min_i32_e32 v0, v0, v1
	v_max_i32_e32 v1, v3, v2
	v_min_i32_e32 v2, v3, v2
	v_max_i32_e32 v3, v177, v175
	v_min_i32_e32 v175, v177, v175
	v_max_i32_e32 v177, v48, v174
	v_min_i32_e32 v48, v48, v174
; __device__ __forceinline__ void sort16p(int (&v)[16]) {
; #pragma unroll
;   for (int k = 2; k <= 16; k <<= 1)
; #pragma unroll
;     for (int j = k >> 1; j > 0; j >>= 1)
; #pragma unroll
;       for (int i = 0; i < 16; ++i) {
;         int l = i ^ j;
;         if (l > i) {
;           if ((i & k) == 0) { CE1(v[i], v[l]); }
;           else { CE1(v[l], v[i]); }
;         }
;       }
; }
	v_max_i32_e32 v174, v14, v176
	v_min_i32_e32 v14, v14, v176
	v_max_i32_e32 v176, v13, v12
	v_min_i32_e32 v12, v13, v12
	v_max_i32_e32 v13, v15, v6
	v_min_i32_e32 v6, v15, v6
	v_max_i32_e32 v15, v4, v5
	v_min_i32_e32 v4, v4, v5
	v_max_i32_e32 v5, v2, v7
	v_min_i32_e32 v2, v2, v7
	v_max_i32_e32 v7, v1, v0
	v_min_i32_e32 v0, v1, v0
	v_max_i32_e32 v1, v3, v177
	v_min_i32_e32 v3, v3, v177
	v_max_i32_e32 v177, v175, v48
	v_min_i32_e32 v48, v175, v48
	v_max_i32_e32 v175, v12, v14
	v_min_i32_e32 v12, v12, v14
	v_max_i32_e32 v14, v176, v174
	v_min_i32_e32 v174, v176, v174
	v_max_i32_e32 v176, v13, v15
	v_min_i32_e32 v13, v13, v15
	v_max_i32_e32 v15, v6, v4
	v_min_i32_e32 v4, v6, v4
	v_max_i32_e32 v6, v0, v2
	v_min_i32_e32 v0, v0, v2
	v_max_i32_e32 v2, v7, v5
	v_min_i32_e32 v5, v7, v5
	v_max_i32_e32 v7, v1, v12
	v_min_i32_e32 v1, v1, v12
	v_max_i32_e32 v12, v3, v175
	v_min_i32_e32 v3, v3, v175
	v_max_i32_e32 v175, v177, v174
	v_min_i32_e32 v174, v177, v174
	v_max_i32_e32 v177, v48, v14
	v_min_i32_e32 v14, v48, v14
	v_max_i32_e32 v48, v0, v176
	v_min_i32_e32 v0, v0, v176
	v_max_i32_e32 v176, v6, v13
	v_min_i32_e32 v6, v6, v13
	v_max_i32_e32 v13, v5, v15
	v_min_i32_e32 v5, v5, v15
	v_max_i32_e32 v15, v2, v4
	v_min_i32_e32 v2, v2, v4
	v_max_i32_e32 v4, v7, v175
	v_min_i32_e32 v7, v7, v175
	v_max_i32_e32 v175, v12, v177
	v_min_i32_e32 v12, v12, v177
	v_max_i32_e32 v177, v1, v174
	v_min_i32_e32 v1, v1, v174
	v_max_i32_e32 v174, v3, v14
	v_min_i32_e32 v3, v3, v14
	v_max_i32_e32 v14, v5, v0
	v_min_i32_e32 v0, v5, v0
	v_max_i32_e32 v5, v2, v6
	v_min_i32_e32 v2, v2, v6
	v_max_i32_e32 v6, v13, v48
	v_min_i32_e32 v13, v13, v48
	v_max_i32_e32 v48, v15, v176
	v_min_i32_e32 v15, v15, v176
	v_max_i32_e32 v176, v4, v175
	v_min_i32_e32 v4, v4, v175
	v_max_i32_e32 v175, v7, v12
	v_min_i32_e32 v7, v7, v12
	v_max_i32_e32 v12, v177, v174
	v_min_i32_e32 v174, v177, v174
	v_max_i32_e32 v177, v1, v3
	v_min_i32_e32 v1, v1, v3
	v_max_i32_e32 v3, v2, v0
	v_min_i32_e32 v0, v2, v0
	v_max_i32_e32 v2, v5, v14
	v_min_i32_e32 v5, v5, v14
	v_max_i32_e32 v14, v15, v13
	v_min_i32_e32 v13, v15, v13
	v_max_i32_e32 v15, v48, v6
	v_min_i32_e32 v6, v48, v6
	v_max_i32_e32 v48, v176, v0
	v_min_i32_e32 v0, v176, v0
	v_max_i32_e32 v176, v4, v3
	v_min_i32_e32 v3, v4, v3
	v_max_i32_e32 v4, v175, v5
	v_min_i32_e32 v5, v175, v5
	v_max_i32_e32 v175, v7, v2
	v_min_i32_e32 v2, v7, v2
	v_max_i32_e32 v7, v12, v13
	v_min_i32_e32 v12, v12, v13
	v_max_i32_e32 v13, v174, v14
	v_min_i32_e32 v14, v174, v14
	v_max_i32_e32 v174, v177, v6
	v_min_i32_e32 v6, v177, v6
	v_max_i32_e32 v177, v1, v15
	v_min_i32_e32 v1, v1, v15
	v_max_i32_e32 v15, v48, v7
	v_min_i32_e32 v7, v48, v7
	v_max_i32_e32 v48, v176, v13
	v_min_i32_e32 v13, v176, v13
	v_max_i32_e32 v176, v4, v174
	v_min_i32_e32 v4, v4, v174
	v_max_i32_e32 v174, v175, v177
	v_min_i32_e32 v175, v175, v177
	v_max_i32_e32 v177, v0, v12
	v_min_i32_e32 v0, v0, v12
	v_max_i32_e32 v12, v3, v14
	v_min_i32_e32 v3, v3, v14
	v_max_i32_e32 v14, v5, v6
	v_min_i32_e32 v5, v5, v6
	v_max_i32_e32 v6, v2, v1
	v_min_i32_e32 v1, v2, v1
	v_max_i32_e32 v2, v15, v176
	v_min_i32_e32 v15, v15, v176
	v_max_i32_e32 v176, v48, v174
	v_min_i32_e32 v48, v48, v174
	v_max_i32_e32 v174, v7, v4
	v_min_i32_e32 v4, v7, v4
	v_max_i32_e32 v7, v13, v175
	v_min_i32_e32 v13, v13, v175
	v_max_i32_e32 v175, v177, v14
	v_min_i32_e32 v14, v177, v14
	v_max_i32_e32 v177, v12, v6
	v_min_i32_e32 v6, v12, v6
	v_max_i32_e32 v12, v0, v5
	v_min_i32_e32 v0, v0, v5
	v_max_i32_e32 v5, v3, v1
	v_min_i32_e32 v1, v3, v1
	v_min_i32_e32 v3, v2, v176
	v_min_i32_e32 v178, v15, v48
	v_min_i32_e32 v179, v174, v7
	v_min_i32_e32 v180, v4, v13
	v_min_i32_e32 v181, v175, v177
	v_min_i32_e32 v182, v14, v6
	v_min_i32_e32 v183, v12, v5
	v_min_i32_e32 v184, v0, v1
	v_max_i32_e32 v185, v162, v163
	v_min_i32_e32 v162, v162, v163
	v_max_i32_e32 v163, v165, v164
	v_min_i32_e32 v164, v165, v164
	v_max_i32_e32 v165, v166, v167
	v_min_i32_e32 v166, v166, v167
	v_max_i32_e32 v167, v169, v168
	v_min_i32_e32 v168, v169, v168
	v_max_i32_e32 v169, v8, v9
	v_min_i32_e32 v8, v8, v9
	v_max_i32_e32 v9, v11, v10
	v_min_i32_e32 v10, v11, v10
	v_max_i32_e32 v11, v170, v171
	v_min_i32_e32 v170, v170, v171
	v_max_i32_e32 v171, v173, v172
	v_min_i32_e32 v172, v173, v172
	v_max_i32_e32 v173, v185, v164
	v_min_i32_e32 v164, v185, v164
	v_max_i32_e32 v185, v162, v163
	v_min_i32_e32 v162, v162, v163
	v_max_i32_e32 v163, v168, v165
	v_min_i32_e32 v165, v168, v165
	v_max_i32_e32 v168, v167, v166
	v_min_i32_e32 v166, v167, v166
	v_max_i32_e32 v167, v169, v10
	v_min_i32_e32 v10, v169, v10
	v_max_i32_e32 v169, v8, v9
	v_min_i32_e32 v8, v8, v9
	v_max_i32_e32 v9, v172, v11
	v_min_i32_e32 v11, v172, v11
	v_max_i32_e32 v172, v171, v170
	v_min_i32_e32 v170, v171, v170
	v_max_i32_e32 v171, v173, v185
	v_min_i32_e32 v173, v173, v185
	v_max_i32_e32 v185, v164, v162
	v_min_i32_e32 v162, v164, v162
	v_max_i32_e32 v164, v166, v165
	v_min_i32_e32 v165, v166, v165
	v_max_i32_e32 v166, v168, v163
	v_min_i32_e32 v163, v168, v163
	v_max_i32_e32 v168, v167, v169
	v_min_i32_e32 v167, v167, v169
	v_max_i32_e32 v169, v10, v8
	v_min_i32_e32 v8, v10, v8
	v_max_i32_e32 v10, v170, v11
	v_min_i32_e32 v11, v170, v11
	v_max_i32_e32 v170, v172, v9
	v_min_i32_e32 v9, v172, v9
	v_max_i32_e32 v172, v171, v165
	v_min_i32_e32 v165, v171, v165
	v_max_i32_e32 v171, v173, v164
	v_min_i32_e32 v164, v173, v164
	v_max_i32_e32 v173, v185, v163
	v_min_i32_e32 v163, v185, v163
	v_max_i32_e32 v185, v162, v166
	v_min_i32_e32 v162, v162, v166
	v_max_i32_e32 v166, v11, v168
	v_min_i32_e32 v11, v11, v168
	v_max_i32_e32 v168, v10, v167
	v_min_i32_e32 v10, v10, v167
	v_max_i32_e32 v167, v9, v169
; __device__ __forceinline__ void sort16p(int (&v)[16]) {
; #pragma unroll
;   for (int k = 2; k <= 16; k <<= 1)
; #pragma unroll
;     for (int j = k >> 1; j > 0; j >>= 1)
; #pragma unroll
;       for (int i = 0; i < 16; ++i) {
;         int l = i ^ j;
;         if (l > i) {
;           if ((i & k) == 0) { CE1(v[i], v[l]); }
;           else { CE1(v[l], v[i]); }
;         }
;       }
; }
; __device__ __forceinline__ void merge16p(int (&a)[16], const int (&b)[16]) {
; #pragma unroll
;   for (int i = 0; i < 16; ++i) a[i] = max(a[i], b[15 - i]);
; #pragma unroll
;   for (int j = 8; j > 0; j >>= 1)
; #pragma unroll
;     for (int i = 0; i < 16; ++i) {
;       int l = i ^ j;
;       if (l > i) { CE1(a[i], a[l]); }
;     }
; }
; __device__ __forceinline__ void xmerge16p(int (&a)[16], int mask) {
;   int b[16];
; #pragma unroll
;   for (int i = 0; i < 16; ++i) b[i] = (mask == 16) ? __builtin_amdgcn_ds_swizzle(a[i], 0x401F) : __shfl_xor(a[i], 32);
;   merge16p(a, b);
; }
	v_min_i32_e32 v9, v9, v169
	v_max_i32_e32 v169, v170, v8
	v_min_i32_e32 v8, v170, v8
	v_max_i32_e32 v170, v172, v173
	v_min_i32_e32 v172, v172, v173
	v_max_i32_e32 v173, v171, v185
	v_min_i32_e32 v171, v171, v185
	v_max_i32_e32 v185, v165, v163
	v_min_i32_e32 v163, v165, v163
	v_max_i32_e32 v165, v164, v162
	v_min_i32_e32 v162, v164, v162
	v_max_i32_e32 v164, v9, v11
	v_min_i32_e32 v9, v9, v11
	v_max_i32_e32 v11, v8, v10
	v_min_i32_e32 v8, v8, v10
	v_max_i32_e32 v10, v167, v166
	v_min_i32_e32 v166, v167, v166
	v_max_i32_e32 v167, v169, v168
	v_min_i32_e32 v168, v169, v168
	v_max_i32_e32 v169, v170, v173
	v_min_i32_e32 v170, v170, v173
	v_max_i32_e32 v173, v172, v171
	v_min_i32_e32 v171, v172, v171
	v_max_i32_e32 v172, v185, v165
	v_min_i32_e32 v165, v185, v165
	v_max_i32_e32 v185, v163, v162
	v_min_i32_e32 v162, v163, v162
	v_max_i32_e32 v163, v8, v9
	v_min_i32_e32 v8, v8, v9
	v_max_i32_e32 v9, v11, v164
	v_min_i32_e32 v11, v11, v164
	v_max_i32_e32 v164, v168, v166
	v_min_i32_e32 v166, v168, v166
	v_max_i32_e32 v168, v167, v10
	v_min_i32_e32 v10, v167, v10
	v_max_i32_e32 v167, v169, v8
	v_min_i32_e32 v8, v169, v8
	v_max_i32_e32 v169, v170, v163
	v_min_i32_e32 v163, v170, v163
	v_max_i32_e32 v170, v173, v11
	v_min_i32_e32 v11, v173, v11
	v_max_i32_e32 v173, v171, v9
	v_min_i32_e32 v9, v171, v9
	v_max_i32_e32 v171, v172, v166
	v_min_i32_e32 v166, v172, v166
	v_max_i32_e32 v172, v165, v164
	v_min_i32_e32 v164, v165, v164
	v_max_i32_e32 v165, v185, v10
	v_min_i32_e32 v10, v185, v10
	v_max_i32_e32 v185, v162, v168
	v_min_i32_e32 v162, v162, v168
	v_max_i32_e32 v168, v167, v171
	v_min_i32_e32 v167, v167, v171
	v_max_i32_e32 v171, v169, v172
	v_min_i32_e32 v169, v169, v172
	v_max_i32_e32 v172, v170, v165
	v_min_i32_e32 v165, v170, v165
	v_max_i32_e32 v170, v173, v185
	v_min_i32_e32 v173, v173, v185
	v_max_i32_e32 v185, v8, v166
	v_min_i32_e32 v8, v8, v166
	v_max_i32_e32 v166, v163, v164
	v_min_i32_e32 v163, v163, v164
	v_max_i32_e32 v164, v11, v10
	v_min_i32_e32 v10, v11, v10
	v_max_i32_e32 v11, v9, v162
	v_min_i32_e32 v9, v9, v162
	v_max_i32_e32 v162, v168, v172
	v_min_i32_e32 v168, v168, v172
	v_max_i32_e32 v172, v171, v170
	v_min_i32_e32 v170, v171, v170
	v_max_i32_e32 v171, v167, v165
	v_min_i32_e32 v165, v167, v165
	v_max_i32_e32 v167, v169, v173
	v_min_i32_e32 v169, v169, v173
	v_max_i32_e32 v173, v185, v164
	v_min_i32_e32 v164, v185, v164
	v_max_i32_e32 v185, v166, v11
	v_min_i32_e32 v11, v166, v11
	v_max_i32_e32 v166, v8, v10
	v_min_i32_e32 v8, v8, v10
	v_max_i32_e32 v10, v163, v9
	v_min_i32_e32 v9, v163, v9
	v_min_i32_e32 v163, v162, v172
	v_min_i32_e32 v186, v168, v170
	v_min_i32_e32 v187, v171, v167
	v_min_i32_e32 v188, v165, v169
	v_min_i32_e32 v189, v173, v185
	v_min_i32_e32 v190, v164, v11
	v_min_i32_e32 v191, v166, v10
	v_min_i32_e32 v192, v8, v9
	v_max3_i32 v2, v2, v176, v192
	v_max3_i32 v3, v3, v8, v9
	v_max3_i32 v8, v15, v48, v191
	v_max3_i32 v9, v178, v166, v10
	v_max3_i32 v7, v174, v7, v190
	v_max3_i32 v10, v179, v164, v11
	v_max3_i32 v4, v4, v13, v189
	v_max3_i32 v11, v180, v173, v185
	v_max3_i32 v13, v175, v177, v188
	v_max3_i32 v15, v181, v165, v169
	v_max3_i32 v6, v14, v6, v187
	v_max3_i32 v14, v182, v171, v167
	v_max3_i32 v5, v12, v5, v186
	v_max3_i32 v12, v183, v168, v170
	v_max3_i32 v0, v0, v1, v163
	v_max3_i32 v1, v184, v162, v172
	v_max_i32_e32 v48, v2, v13
	v_min_i32_e32 v2, v2, v13
	v_max_i32_e32 v13, v3, v15
	v_min_i32_e32 v3, v3, v15
	v_max_i32_e32 v15, v8, v6
	v_min_i32_e32 v6, v8, v6
	v_max_i32_e32 v8, v9, v14
	v_min_i32_e32 v9, v9, v14
	v_max_i32_e32 v14, v7, v5
	v_min_i32_e32 v5, v7, v5
	v_max_i32_e32 v7, v10, v12
	v_min_i32_e32 v10, v10, v12
	v_max_i32_e32 v12, v4, v0
	v_min_i32_e32 v0, v4, v0
	v_max_i32_e32 v4, v11, v1
	v_min_i32_e32 v1, v11, v1
	v_max_i32_e32 v11, v48, v14
	v_min_i32_e32 v14, v48, v14
	v_max_i32_e32 v48, v13, v7
	v_min_i32_e32 v7, v13, v7
	v_max_i32_e32 v13, v15, v12
	v_min_i32_e32 v12, v15, v12
	v_max_i32_e32 v15, v8, v4
	v_min_i32_e32 v4, v8, v4
	v_max_i32_e32 v8, v2, v5
	v_min_i32_e32 v2, v2, v5
	v_max_i32_e32 v5, v3, v10
	v_min_i32_e32 v3, v3, v10
	v_max_i32_e32 v10, v6, v0
	v_min_i32_e32 v0, v6, v0
	v_max_i32_e32 v6, v9, v1
	v_min_i32_e32 v1, v9, v1
	v_max_i32_e32 v9, v11, v13
	v_min_i32_e32 v11, v11, v13
	v_max_i32_e32 v13, v48, v15
	v_min_i32_e32 v15, v48, v15
	v_max_i32_e32 v48, v14, v12
	v_min_i32_e32 v12, v14, v12
	v_max_i32_e32 v14, v7, v4
	v_min_i32_e32 v4, v7, v4
	v_max_i32_e32 v7, v8, v10
	v_min_i32_e32 v8, v8, v10
	v_max_i32_e32 v10, v5, v6
	v_min_i32_e32 v5, v5, v6
	v_max_i32_e32 v6, v2, v0
	v_min_i32_e32 v0, v2, v0
	v_max_i32_e32 v2, v3, v1
	v_min_i32_e32 v1, v3, v1
	v_max_i32_e32 v3, v9, v13
	v_min_i32_e32 v9, v9, v13
	v_max_i32_e32 v13, v11, v15
	v_min_i32_e32 v11, v11, v15
	v_max_i32_e32 v15, v48, v14
	v_min_i32_e32 v14, v48, v14
	v_max_i32_e32 v48, v12, v4
	v_min_i32_e32 v4, v12, v4
	v_max_i32_e32 v12, v7, v10
	v_min_i32_e32 v7, v7, v10
	v_max_i32_e32 v10, v8, v5
	v_min_i32_e32 v5, v8, v5
	v_max_i32_e32 v8, v6, v2
	v_min_i32_e32 v2, v6, v2
	v_max_i32_e32 v6, v0, v1
	v_min_i32_e32 v0, v0, v1
	ds_swizzle_b32 v1, v3 offset:swizzle(SWAP,16)
	ds_swizzle_b32 v162, v9 offset:swizzle(SWAP,16)
	ds_swizzle_b32 v163, v13 offset:swizzle(SWAP,16)
	ds_swizzle_b32 v164, v11 offset:swizzle(SWAP,16)
	ds_swizzle_b32 v165, v15 offset:swizzle(SWAP,16)
	ds_swizzle_b32 v166, v14 offset:swizzle(SWAP,16)
	ds_swizzle_b32 v167, v48 offset:swizzle(SWAP,16)
	ds_swizzle_b32 v168, v4 offset:swizzle(SWAP,16)
	ds_swizzle_b32 v169, v12 offset:swizzle(SWAP,16)
	ds_swizzle_b32 v170, v7 offset:swizzle(SWAP,16)
	ds_swizzle_b32 v171, v10 offset:swizzle(SWAP,16)
	ds_swizzle_b32 v172, v0 offset:swizzle(SWAP,16)
	ds_swizzle_b32 v173, v6 offset:swizzle(SWAP,16)
	ds_swizzle_b32 v174, v2 offset:swizzle(SWAP,16)
	ds_swizzle_b32 v175, v8 offset:swizzle(SWAP,16)
	ds_swizzle_b32 v176, v5 offset:swizzle(SWAP,16)
	s_waitcnt lgkmcnt(4)
; __device__ __forceinline__ void merge16p(int (&a)[16], const int (&b)[16]) {
; #pragma unroll
;   for (int i = 0; i < 16; ++i) a[i] = max(a[i], b[15 - i]);
; #pragma unroll
;   for (int j = 8; j > 0; j >>= 1)
; #pragma unroll
;     for (int i = 0; i < 16; ++i) {
;       int l = i ^ j;
;       if (l > i) { CE1(a[i], a[l]); }
;     }
; }
; __device__ __forceinline__ void xmerge16p(int (&a)[16], int mask) {
;   int b[16];
; #pragma unroll
;   for (int i = 0; i < 16; ++i) b[i] = (mask == 16) ? __builtin_amdgcn_ds_swizzle(a[i], 0x401F) : __shfl_xor(a[i], 32);
;   merge16p(a, b);
; }
	v_max_i32_e32 v3, v3, v172
	s_waitcnt lgkmcnt(3)
	v_max_i32_e32 v9, v9, v173
	s_waitcnt lgkmcnt(2)
	v_max_i32_e32 v13, v13, v174
	s_waitcnt lgkmcnt(1)
	v_max_i32_e32 v11, v11, v175
	s_waitcnt lgkmcnt(0)
	v_max_i32_e32 v15, v15, v176
	v_max_i32_e32 v14, v14, v171
	v_max_i32_e32 v48, v48, v170
	v_max_i32_e32 v4, v4, v169
	v_max_i32_e32 v12, v12, v168
	v_max_i32_e32 v7, v7, v167
	v_max_i32_e32 v10, v10, v166
	v_max_i32_e32 v5, v5, v165
	v_max_i32_e32 v8, v8, v164
	v_max_i32_e32 v2, v2, v163
	v_max_i32_e32 v6, v6, v162
	v_max_i32_e32 v0, v0, v1
	v_max_i32_e32 v1, v3, v12
	v_min_i32_e32 v3, v3, v12
	v_max_i32_e32 v12, v9, v7
	v_min_i32_e32 v7, v9, v7
	v_max_i32_e32 v9, v13, v10
	v_min_i32_e32 v10, v13, v10
	v_max_i32_e32 v13, v11, v5
	v_min_i32_e32 v5, v11, v5
	v_max_i32_e32 v11, v15, v8
	v_min_i32_e32 v8, v15, v8
	v_max_i32_e32 v15, v14, v2
	v_min_i32_e32 v2, v14, v2
	v_max_i32_e32 v14, v48, v6
	v_min_i32_e32 v6, v48, v6
	v_max_i32_e32 v48, v4, v0
	v_min_i32_e32 v0, v4, v0
	v_max_i32_e32 v4, v1, v11
	v_min_i32_e32 v1, v1, v11
	v_max_i32_e32 v11, v12, v15
	v_min_i32_e32 v12, v12, v15
	v_max_i32_e32 v15, v9, v14
	v_min_i32_e32 v9, v9, v14
	v_max_i32_e32 v14, v13, v48
	v_min_i32_e32 v13, v13, v48
	v_max_i32_e32 v48, v3, v8
	v_min_i32_e32 v3, v3, v8
	v_max_i32_e32 v8, v7, v2
	v_min_i32_e32 v2, v7, v2
	v_max_i32_e32 v7, v10, v6
	v_min_i32_e32 v6, v10, v6
	v_max_i32_e32 v10, v5, v0
	v_min_i32_e32 v0, v5, v0
	v_max_i32_e32 v5, v4, v15
	v_min_i32_e32 v4, v4, v15
	v_max_i32_e32 v15, v11, v14
	v_min_i32_e32 v11, v11, v14
	v_max_i32_e32 v14, v1, v9
	v_min_i32_e32 v1, v1, v9
	v_max_i32_e32 v9, v12, v13
	v_min_i32_e32 v12, v12, v13
	v_max_i32_e32 v13, v48, v7
	v_min_i32_e32 v7, v48, v7
	v_max_i32_e32 v48, v8, v10
	v_min_i32_e32 v8, v8, v10
	v_max_i32_e32 v10, v3, v6
	v_min_i32_e32 v3, v3, v6
	v_max_i32_e32 v6, v2, v0
	v_min_i32_e32 v0, v2, v0
	v_max_i32_e32 v2, v5, v15
	v_min_i32_e32 v5, v5, v15
	v_max_i32_e32 v15, v4, v11
	v_min_i32_e32 v4, v4, v11
	v_max_i32_e32 v11, v14, v9
	v_min_i32_e32 v9, v14, v9
	v_max_i32_e32 v14, v1, v12
	v_min_i32_e32 v1, v1, v12
	v_max_i32_e32 v12, v13, v48
	v_min_i32_e32 v13, v13, v48
	v_max_i32_e32 v48, v7, v8
	v_min_i32_e32 v7, v7, v8
	v_max_i32_e32 v8, v10, v6
	v_min_i32_e32 v6, v10, v6
	v_max_i32_e32 v10, v3, v0
	v_min_i32_e32 v0, v3, v0
	ds_bpermute_b32 v3, v54, v2
	ds_bpermute_b32 v162, v54, v5
	ds_bpermute_b32 v163, v54, v15
	ds_bpermute_b32 v164, v54, v4
	ds_bpermute_b32 v165, v54, v11
	ds_bpermute_b32 v166, v54, v9
	ds_bpermute_b32 v167, v54, v14
	ds_bpermute_b32 v168, v54, v1
	ds_bpermute_b32 v169, v54, v12
	ds_bpermute_b32 v170, v54, v13
	ds_bpermute_b32 v171, v54, v48
	ds_bpermute_b32 v172, v54, v0
	ds_bpermute_b32 v173, v54, v10
	ds_bpermute_b32 v174, v54, v6
	ds_bpermute_b32 v175, v54, v8
	ds_bpermute_b32 v176, v54, v7
	s_waitcnt lgkmcnt(4)
	v_max_i32_e32 v2, v2, v172
	s_waitcnt lgkmcnt(3)
	v_max_i32_e32 v5, v5, v173
	s_waitcnt lgkmcnt(2)
	v_max_i32_e32 v15, v15, v174
	s_waitcnt lgkmcnt(1)
	v_max_i32_e32 v4, v4, v175
	s_waitcnt lgkmcnt(0)
; __device__ void ph_score(const P& p, int* lds) {
;     ...
;       int idx4[4];
; #pragma unroll
;       for (int i = 0; i < 16; ++i) {
;         const int k = key_unmap(a[i]);
;         tv[half][i] = __int_as_float(k & ~0x7f);
;         if ((i >> 2) == 0) idx4[i & 3] = k & 0x7f;
;       }
; #pragma unroll
;       for (int i = 4; i < 16; ++i) {
;         const int k = key_unmap(a[i]) & 0x7f;
;         if ((i >> 2) == 1) idx4[i & 3] = (fq == 1) ? k : idx4[i & 3];
;         if ((i >> 2) == 2) idx4[i & 3] = (fq == 2) ? k : idx4[i & 3];
;         if ((i >> 2) == 3) idx4[i & 3] = (fq == 3) ? k : idx4[i & 3];
;       }
;       *(int4*)(myl + half * 16 + fq * 4) = make_int4(idx4[0], idx4[1], idx4[2], idx4[3]);
;     }
;     int L0[16];
; #pragma unroll
;     for (int rr = 0; rr < 4; ++rr) {
;       const float v1 = fq == 0 ? tv[0][rr] : (fq == 1 ? tv[0][4 + rr] : (fq == 2 ? tv[0][8 + rr] : tv[0][12 + rr]));
;       int Lr[16];
; #pragma unroll
;       for (int j = 0; j < 16; ++j) Lr[j] = key_pack(v1 + tv[1][j], ((fq * 4 + rr) << 4) | j, 0xff);
	v_max_i32_e32 v11, v11, v176
	v_max_i32_e32 v9, v9, v171
	v_max_i32_e32 v14, v14, v170
	v_max_i32_e32 v1, v1, v169
	v_max_i32_e32 v12, v12, v168
	v_max_i32_e32 v13, v13, v167
	v_max_i32_e32 v48, v48, v166
	v_max_i32_e32 v7, v7, v165
	v_max_i32_e32 v8, v8, v164
	v_max_i32_e32 v6, v6, v163
	v_max_i32_e32 v10, v10, v162
	v_max_i32_e32 v0, v0, v3
	v_max_i32_e32 v3, v2, v12
	v_min_i32_e32 v2, v2, v12
	v_max_i32_e32 v12, v5, v13
	v_min_i32_e32 v5, v5, v13
	v_max_i32_e32 v13, v15, v48
	v_min_i32_e32 v15, v15, v48
	v_max_i32_e32 v48, v4, v7
	v_min_i32_e32 v4, v4, v7
	v_max_i32_e32 v7, v11, v8
	v_min_i32_e32 v8, v11, v8
	v_max_i32_e32 v11, v9, v6
	v_min_i32_e32 v6, v9, v6
	v_max_i32_e32 v9, v14, v10
	v_min_i32_e32 v10, v14, v10
	v_max_i32_e32 v14, v1, v0
	v_min_i32_e32 v0, v1, v0
	v_max_i32_e32 v1, v3, v7
	v_min_i32_e32 v3, v3, v7
	v_max_i32_e32 v7, v12, v11
	v_min_i32_e32 v11, v12, v11
	v_max_i32_e32 v12, v13, v9
	v_min_i32_e32 v9, v13, v9
	v_max_i32_e32 v13, v48, v14
	v_min_i32_e32 v14, v48, v14
	v_max_i32_e32 v48, v2, v8
	v_min_i32_e32 v2, v2, v8
	v_max_i32_e32 v8, v5, v6
	v_min_i32_e32 v5, v5, v6
	v_max_i32_e32 v6, v15, v10
	v_min_i32_e32 v10, v15, v10
	v_max_i32_e32 v15, v4, v0
	v_min_i32_e32 v0, v4, v0
	v_max_i32_e32 v4, v1, v12
	v_min_i32_e32 v1, v1, v12
	v_max_i32_e32 v12, v7, v13
	v_min_i32_e32 v7, v7, v13
	v_max_i32_e32 v13, v3, v9
	v_min_i32_e32 v3, v3, v9
	v_max_i32_e32 v9, v11, v14
	v_min_i32_e32 v11, v11, v14
	v_max_i32_e32 v14, v48, v6
	v_min_i32_e32 v48, v48, v6
	v_max_i32_e32 v6, v8, v15
	v_min_i32_e32 v8, v8, v15
	v_max_i32_e32 v162, v2, v10
	v_min_i32_e32 v2, v2, v10
	v_max_i32_e32 v163, v5, v0
	v_min_i32_e32 v0, v5, v0
	v_max_i32_e32 v165, v4, v12
	v_min_i32_e32 v12, v4, v12
	v_max_i32_e32 v166, v1, v7
	v_min_i32_e32 v167, v1, v7
	v_max_i32_e32 v4, v13, v9
	v_min_i32_e32 v5, v13, v9
	v_max_i32_e32 v10, v3, v11
	v_min_i32_e32 v3, v3, v11
	v_max_i32_e32 v15, v14, v6
	v_min_i32_e32 v14, v14, v6
	v_max_i32_e32 v6, v48, v8
	v_min_i32_e32 v1, v48, v8
	v_max_i32_e32 v164, v162, v163
	v_min_i32_e32 v163, v162, v163
	v_max_i32_e32 v162, v2, v0
	v_min_i32_e32 v9, v2, v0
	v_ashrrev_i32_e32 v0, 31, v165
	v_and_b32_e32 v7, 0x7fffffff, v0
	v_bitop3_b32 v2, v0, v165, s75 bitop3:0x6c
	v_bitop3_b32 v0, v7, s80, v165 bitop3:0x48
	v_ashrrev_i32_e32 v165, 31, v4
	v_ashrrev_i32_e32 v7, 31, v12
	v_bitop3_b32 v165, v165, s80, v4 bitop3:0x48
	v_and_b32_e32 v8, 0x7fffffff, v7
	v_cndmask_b32_e64 v0, v0, v165, s[6:7]
	v_ashrrev_i32_e32 v165, 31, v5
	v_bitop3_b32 v8, v8, s80, v12 bitop3:0x48
	v_ashrrev_i32_e32 v11, 31, v166
	v_bitop3_b32 v165, v165, s80, v5 bitop3:0x48
	v_and_b32_e32 v13, 0x7fffffff, v11
	v_cndmask_b32_e64 v8, v8, v165, s[6:7]
	v_ashrrev_i32_e32 v165, 31, v10
	v_bitop3_b32 v7, v7, v12, s75 bitop3:0x6c
	v_bitop3_b32 v12, v11, v166, s75 bitop3:0x6c
	v_bitop3_b32 v11, v13, s80, v166 bitop3:0x48
	v_ashrrev_i32_e32 v13, 31, v167
	v_bitop3_b32 v165, v165, s80, v10 bitop3:0x48
	v_and_b32_e32 v48, 0x7fffffff, v13
	v_cndmask_b32_e64 v11, v11, v165, s[6:7]
	v_ashrrev_i32_e32 v165, 31, v3
	v_bitop3_b32 v48, v48, s80, v167 bitop3:0x48
	v_bitop3_b32 v165, v165, s80, v3 bitop3:0x48
	v_cndmask_b32_e64 v48, v48, v165, s[6:7]
	v_ashrrev_i32_e32 v165, 31, v15
	v_bitop3_b32 v165, v165, s80, v15 bitop3:0x48
	v_cndmask_b32_e64 v0, v0, v165, s[4:5]
	v_ashrrev_i32_e32 v165, 31, v14
	v_bitop3_b32 v165, v165, s80, v14 bitop3:0x48
	v_cndmask_b32_e64 v8, v8, v165, s[4:5]
	v_ashrrev_i32_e32 v165, 31, v6
	v_bitop3_b32 v165, v165, s80, v6 bitop3:0x48
	v_cndmask_b32_e64 v11, v11, v165, s[4:5]
	v_ashrrev_i32_e32 v165, 31, v1
	v_bitop3_b32 v165, v165, s80, v1 bitop3:0x48
	v_cndmask_b32_e64 v48, v48, v165, s[4:5]
	v_ashrrev_i32_e32 v165, 31, v164
	v_bitop3_b32 v165, v165, s80, v164 bitop3:0x48
	v_cndmask_b32_e64 v166, v0, v165, s[0:1]
	v_ashrrev_i32_e32 v0, 31, v163
	v_bitop3_b32 v0, v0, s80, v163 bitop3:0x48
	v_bitop3_b32 v13, v13, v167, s75 bitop3:0x6c
	v_cndmask_b32_e64 v167, v8, v0, s[0:1]
	v_ashrrev_i32_e32 v0, 31, v162
	v_bitop3_b32 v0, v0, s80, v162 bitop3:0x48
	v_cndmask_b32_e64 v168, v11, v0, s[0:1]
	v_ashrrev_i32_e32 v0, 31, v9
	v_bitop3_b32 v0, v0, s80, v9 bitop3:0x48
	v_cmp_gt_i32_e64 s[54:55], 0, v5
	v_cmp_gt_i32_e64 s[56:57], 0, v4
	v_cmp_gt_i32_e64 s[50:51], 0, v3
	v_cmp_gt_i32_e64 s[52:53], 0, v10
	v_cmp_gt_i32_e64 s[48:49], 0, v15
	v_cmp_gt_i32_e64 s[42:43], 0, v14
	v_cmp_gt_i32_e64 s[44:45], 0, v1
	v_cmp_gt_i32_e64 s[46:47], 0, v6
	v_cmp_gt_i32_e64 s[40:41], 0, v164
	v_cmp_gt_i32_e64 s[38:39], 0, v163
	v_cmp_gt_i32_e64 s[36:37], 0, v162
	v_cmp_gt_i32_e64 s[34:35], 0, v9
	v_cndmask_b32_e64 v169, v48, v0, s[0:1]
	v_cmp_lt_i32_e64 s[58:59], 1, v21
	ds_write_b128 v150, v[166:169] offset:64
	s_and_saveexec_b64 s[62:63], s[58:59]
	s_xor_b64 s[78:79], exec, s[62:63]
	s_cbranch_execz .LBB0_764
	v_cmp_lt_i32_e64 s[58:59], 2, v21
	s_and_saveexec_b64 s[62:63], s[58:59]
	s_xor_b64 s[58:59], exec, s[62:63]
	v_cndmask_b32_e64 v0, 0, v151, s[30:31]
	v_bitop3_b32 v48, v0, v160, s33 bitop3:0x78
	s_andn2_saveexec_b64 s[30:31], s[58:59]
	v_cndmask_b32_e64 v0, 0, v151, s[28:29]
	v_bitop3_b32 v48, v0, v159, s33 bitop3:0x78
	s_or_b64 exec, exec, s[30:31]
